# aq2g + lru pass-1 carry prefetch + B1 queue order (small items first, selects longest-first last)
# speedup vs baseline: 1.0074x; 1.0074x over previous
; DI void lru_tile(const Params& p, int layer, int isP, int sq, int tile, int nb, int pass, char*) {
;     ...
;     float h = isP ? 0.f : p.state_lru[(long)(layer * NB_S + sq) * 512 + ch0 + c];
;     for (int i0 = 0; i0 < tile; i0 += 16) {
;       float2 e[16];
; #pragma unroll
;       for (int u = 0; u < 16; ++u)
;         e[u] = (i0 + u < tile) ? *(const float2*)(agg + ((long)(sq * NTILE_P + i0 + u) * 512 + ch0 + c) * 2) : make_float2(1.f, 0.f);
; #pragma unroll
;       for (int u = 0; u < 16; ++u) h = e[u].x * h + e[u].y;
;     }
.LBB0_4761:
	s_or_b64 exec, exec, s[4:5]
	v_bfe_u32 v73, v95, 4, 2
	s_lshl_b32 s10, s47, 4
	s_waitcnt vmcnt(4)
	v_lshlrev_b32_e32 v64, 3, v73
	v_or_b32_e32 v65, s10, v74
	v_mul_lo_u32 v65, v65, s64
	v_lshlrev_b32_e32 v64, 1, v64
	v_add3_u32 v64, s89, v65, v64
	s_waitcnt lgkmcnt(0)
	s_barrier
	s_waitcnt vmcnt(1)
	ds_read_b128 v[68:71], v64 offset:51968
	ds_read_b128 v[64:67], v64 offset:52032
	s_waitcnt vmcnt(0)
	v_lshlrev_b32_e32 v248, 3, v75
	s_mul_i32 s0, s42, 0x41
	s_ashr_i32 s1, s0, 31
	s_lshl_b64 s[0:1], s[0:1], 12
	s_add_u32 s0, s63, s0
	s_addc_u32 s1, s88, s1
	s_sub_u32 s0, s0, 0xe000
	s_subb_u32 s1, s1, 0
	s_cmpk_lt_i32 s45, 1
	s_cbranch_scc1 .Llc_pdone
	global_load_dwordx2 v[132:133], v248, s[0:1] offset:-4096
	global_load_dwordx2 v[134:135], v248, s[0:1]
	s_add_u32 s0, s0, 0x2000
	s_addc_u32 s1, s1, 0
	s_cmpk_lt_i32 s45, 3
	s_cbranch_scc1 .Llc_pdone
	global_load_dwordx2 v[136:137], v248, s[0:1] offset:-4096
	global_load_dwordx2 v[138:139], v248, s[0:1]
	s_add_u32 s0, s0, 0x2000
	s_addc_u32 s1, s1, 0
	s_cmpk_lt_i32 s45, 5
	s_cbranch_scc1 .Llc_pdone
	global_load_dwordx2 v[140:141], v248, s[0:1] offset:-4096
	global_load_dwordx2 v[142:143], v248, s[0:1]
	s_add_u32 s0, s0, 0x2000
	s_addc_u32 s1, s1, 0
	s_cmpk_lt_i32 s45, 7
	s_cbranch_scc1 .Llc_pdone
	global_load_dwordx2 v[144:145], v248, s[0:1] offset:-4096
	global_load_dwordx2 v[146:147], v248, s[0:1]
	s_add_u32 s0, s0, 0x2000
	s_addc_u32 s1, s1, 0
	s_cmpk_lt_i32 s45, 9
	s_cbranch_scc1 .Llc_pdone
	global_load_dwordx2 v[148:149], v248, s[0:1] offset:-4096
	global_load_dwordx2 v[150:151], v248, s[0:1]
	s_add_u32 s0, s0, 0x2000
	s_addc_u32 s1, s1, 0
	s_cmpk_lt_i32 s45, 11
	s_cbranch_scc1 .Llc_pdone
	global_load_dwordx2 v[152:153], v248, s[0:1] offset:-4096
	global_load_dwordx2 v[154:155], v248, s[0:1]
	s_add_u32 s0, s0, 0x2000
	s_addc_u32 s1, s1, 0
	s_cmpk_lt_i32 s45, 13
	s_cbranch_scc1 .Llc_pdone
	global_load_dwordx2 v[156:157], v248, s[0:1] offset:-4096
	global_load_dwordx2 v[180:181], v248, s[0:1]
	s_add_u32 s0, s0, 0x2000
	s_addc_u32 s1, s1, 0
	s_cmpk_lt_i32 s45, 15
	s_cbranch_scc1 .Llc_pdone
	global_load_dwordx2 v[182:183], v248, s[0:1] offset:-4096
	global_load_dwordx2 v[184:185], v248, s[0:1]
	s_add_u32 s0, s0, 0x2000
	s_addc_u32 s1, s1, 0
	s_cmpk_lt_i32 s45, 17
	s_cbranch_scc1 .Llc_pdone
	global_load_dwordx2 v[186:187], v248, s[0:1] offset:-4096
	global_load_dwordx2 v[188:189], v248, s[0:1]
	s_add_u32 s0, s0, 0x2000
	s_addc_u32 s1, s1, 0
	s_cmpk_lt_i32 s45, 19
	s_cbranch_scc1 .Llc_pdone
	global_load_dwordx2 v[190:191], v248, s[0:1] offset:-4096
	global_load_dwordx2 v[192:193], v248, s[0:1]
	s_add_u32 s0, s0, 0x2000
	s_addc_u32 s1, s1, 0
	s_cmpk_lt_i32 s45, 21
	s_cbranch_scc1 .Llc_pdone
	global_load_dwordx2 v[194:195], v248, s[0:1] offset:-4096
	global_load_dwordx2 v[196:197], v248, s[0:1]
	s_add_u32 s0, s0, 0x2000
	s_addc_u32 s1, s1, 0
	s_cmpk_lt_i32 s45, 23
	s_cbranch_scc1 .Llc_pdone
	global_load_dwordx2 v[198:199], v248, s[0:1] offset:-4096
	global_load_dwordx2 v[200:201], v248, s[0:1]
	s_add_u32 s0, s0, 0x2000
	s_addc_u32 s1, s1, 0
	s_cmpk_lt_i32 s45, 25
	s_cbranch_scc1 .Llc_pdone
	global_load_dwordx2 v[202:203], v248, s[0:1] offset:-4096
	global_load_dwordx2 v[204:205], v248, s[0:1]
	s_add_u32 s0, s0, 0x2000
	s_addc_u32 s1, s1, 0
	s_cmpk_lt_i32 s45, 27
	s_cbranch_scc1 .Llc_pdone
	global_load_dwordx2 v[206:207], v248, s[0:1] offset:-4096
	global_load_dwordx2 v[208:209], v248, s[0:1]
	s_add_u32 s0, s0, 0x2000
	s_addc_u32 s1, s1, 0
	s_cmpk_lt_i32 s45, 29
	s_cbranch_scc1 .Llc_pdone
	global_load_dwordx2 v[210:211], v248, s[0:1] offset:-4096
	global_load_dwordx2 v[212:213], v248, s[0:1]
	s_add_u32 s0, s0, 0x2000
	s_addc_u32 s1, s1, 0
	s_cmpk_lt_i32 s45, 31
	s_cbranch_scc1 .Llc_pdone
	global_load_dwordx2 v[214:215], v248, s[0:1] offset:-4096
	global_load_dwordx2 v[216:217], v248, s[0:1]
	s_add_u32 s0, s0, 0x2000
	s_addc_u32 s1, s1, 0
	s_cmpk_lt_i32 s45, 33
	s_cbranch_scc1 .Llc_pdone
	global_load_dwordx2 v[218:219], v248, s[0:1] offset:-4096
	global_load_dwordx2 v[220:221], v248, s[0:1]
	s_add_u32 s0, s0, 0x2000
	s_addc_u32 s1, s1, 0
	s_cmpk_lt_i32 s45, 35
	s_cbranch_scc1 .Llc_pdone
	global_load_dwordx2 v[222:223], v248, s[0:1] offset:-4096
	global_load_dwordx2 v[224:225], v248, s[0:1]
	s_add_u32 s0, s0, 0x2000
	s_addc_u32 s1, s1, 0
	s_cmpk_lt_i32 s45, 37
	s_cbranch_scc1 .Llc_pdone
	global_load_dwordx2 v[226:227], v248, s[0:1] offset:-4096
	global_load_dwordx2 v[228:229], v248, s[0:1]
	s_add_u32 s0, s0, 0x2000
	s_addc_u32 s1, s1, 0
	s_cmpk_lt_i32 s45, 39
	s_cbranch_scc1 .Llc_pdone
	global_load_dwordx2 v[230:231], v248, s[0:1] offset:-4096
	global_load_dwordx2 v[232:233], v248, s[0:1]
	s_add_u32 s0, s0, 0x2000
	s_addc_u32 s1, s1, 0
	s_cmpk_lt_i32 s45, 41
	s_cbranch_scc1 .Llc_pdone
	global_load_dwordx2 v[234:235], v248, s[0:1] offset:-4096
	global_load_dwordx2 v[236:237], v248, s[0:1]
	s_add_u32 s0, s0, 0x2000
	s_addc_u32 s1, s1, 0
	s_cmpk_lt_i32 s45, 43
	s_cbranch_scc1 .Llc_pdone
	global_load_dwordx2 v[238:239], v248, s[0:1] offset:-4096
	global_load_dwordx2 v[240:241], v248, s[0:1]
	s_add_u32 s0, s0, 0x2000
	s_addc_u32 s1, s1, 0
	s_cmpk_lt_i32 s45, 45
	s_cbranch_scc1 .Llc_pdone
	global_load_dwordx2 v[242:243], v248, s[0:1] offset:-4096
	global_load_dwordx2 v[244:245], v248, s[0:1]
; #define MFMA16(a, b, c) __builtin_amdgcn_mfma_f32_16x16x32_bf16((a), (b), (c), 0, 0, 0)
; DI float sigm(float x) { return __builtin_amdgcn_rcpf(1.f + __expf(-x)); }
; DI void lru_tile(const Params& p, int layer, int isP, int sq, int tile, int nb, int pass, char*) {
;     ...
;   {
;     bf16x8 af0 = *(const bf16x8*)(xca + (wid * 16 + fr) * 72 + fq * 8);
;     bf16x8 af1 = *(const bf16x8*)(xca + (wid * 16 + fr) * 72 + 32 + fq * 8);
; #pragma unroll
;     for (int nt = 0; nt < 4; ++nt) {
;       const int d = nt * 16 + fr;
;       const bf16x8 ba0 = wfa0[nt], ba1 = wfa1[nt], bx0 = wfx0[nt], bx1 = wfx1[nt];
;       f32x4 ar = {0.f, 0.f, 0.f, 0.f}, ai = {0.f, 0.f, 0.f, 0.f};
;       ar = MFMA16(af0, ba0, ar); ar = MFMA16(af1, ba1, ar);
;       ai = MFMA16(af0, bx0, ai); ai = MFMA16(af1, bx1, ai);
;       const float bav = pbav[nt], bxv = pbxv[nt];
;       const float sp = log1pf(__expf(-plam[nt]));
; #pragma unroll
;       for (int j = 0; j < 4; ++j) {
;         const int t = wid * 16 + fq * 4 + j;
;         float r = sigm(ar[j] + bav), ig = sigm(ai[j] + bxv);
;         float la = -8.f * r * sp;
;         float a = __expf(la);
;         float b = sqrtf(1.f - __expf(2.f * la)) * (ig * xcs[t * 64 + d]);
;         if (t0 + t >= T) { a = 1.f; b = 0.f; }
;         as_[t * 64 + d] = a;
;         bs_[t * 64 + d] = b;
;       }
;     }
;   }
.Llc_pdone:
	v_mul_f32_e32 v76, 0xbfb8aa3b, v96
	s_waitcnt lgkmcnt(1)
	v_mfma_f32_16x16x32_bf16 v[56:59], v[68:71], v[56:59], 0
	v_exp_f32_e32 v76, v76
	s_mov_b32 s12, 0x3f2aaaab
	s_mov_b32 s13, 0x3f317218
	v_mfma_f32_16x16x32_bf16 v[60:63], v[68:71], v[60:63], 0
	s_mov_b32 s14, 0x7f800000
	s_mov_b32 s15, 0x33800000
	s_mov_b32 s16, 0xf800000
	s_waitcnt lgkmcnt(0)
	v_mfma_f32_16x16x32_bf16 v[56:59], v[64:67], v[48:51], v[56:59]
	s_mov_b32 s11, 0
	v_mfma_f32_16x16x32_bf16 v[48:51], v[64:67], v[52:55], v[60:63]
	v_add_f32_e32 v54, 1.0, v76
	v_add_f32_e32 v52, -1.0, v54
	v_sub_f32_e32 v53, v52, v54
	v_add_f32_e32 v53, 1.0, v53
	v_sub_f32_e32 v52, v76, v52
	v_add_f32_e32 v55, v52, v53
	v_frexp_mant_f32_e32 v60, v54
	v_cvt_f64_f32_e32 v[52:53], v54
	v_frexp_exp_i32_f64_e32 v52, v[52:53]
	v_cmp_gt_f32_e32 vcc, s12, v60
	v_add_f32_e32 v48, v93, v48
	v_mul_f32_e32 v48, 0xbfb8aa3b, v48
	v_subbrev_co_u32_e32 v52, vcc, 0, v52, vcc
	v_sub_u32_e32 v53, 0, v52
	v_ldexp_f32 v54, v54, v53
	v_ldexp_f32 v53, v55, v53
	v_add_f32_e32 v55, -1.0, v54
	v_add_f32_e32 v62, 1.0, v54
	v_add_f32_e32 v60, 1.0, v55
	v_add_f32_e32 v63, -1.0, v62
	v_sub_f32_e32 v60, v54, v60
	v_sub_f32_e32 v54, v54, v63
	v_add_f32_e32 v60, v53, v60
	v_add_f32_e32 v53, v53, v54
	v_add_f32_e32 v54, v62, v53
	v_rcp_f32_e32 v63, v54
	v_add_f32_e32 v61, v55, v60
	v_sub_f32_e32 v55, v61, v55
	v_sub_f32_e32 v55, v60, v55
	v_sub_f32_e32 v60, v54, v62
	v_sub_f32_e32 v53, v53, v60
	v_mul_f32_e32 v60, v61, v63
	v_mul_f32_e32 v62, v54, v60
	v_fma_f32 v77, v60, v54, -v62
	v_fmac_f32_e32 v77, v60, v53
	v_add_f32_e32 v78, v62, v77
	v_sub_f32_e32 v79, v61, v78
	v_sub_f32_e32 v61, v61, v79
	v_sub_f32_e32 v62, v78, v62
	v_sub_f32_e32 v61, v61, v78
	v_add_f32_e32 v55, v55, v61
	v_sub_f32_e32 v61, v62, v77
	v_add_f32_e32 v55, v61, v55
	v_add_f32_e32 v61, v79, v55
	v_mul_f32_e32 v62, v63, v61
	v_mul_f32_e32 v77, v54, v62
	v_fma_f32 v54, v62, v54, -v77
	v_fmac_f32_e32 v54, v62, v53
	v_sub_f32_e32 v53, v79, v61
	v_add_f32_e32 v53, v55, v53
	v_add_f32_e32 v55, v77, v54
	v_sub_f32_e32 v78, v61, v55
	v_sub_f32_e32 v61, v61, v78
	v_sub_f32_e32 v77, v55, v77
	v_sub_f32_e32 v55, v61, v55
	v_add_f32_e32 v53, v53, v55
	v_sub_f32_e32 v54, v77, v54
	v_cvt_f32_i32_e32 v52, v52
	v_add_f32_e32 v53, v54, v53
	v_add_f32_e32 v54, v60, v62
	v_add_f32_e32 v53, v78, v53
	v_sub_f32_e32 v55, v54, v60
	v_mul_f32_e32 v53, v63, v53
	v_sub_f32_e32 v55, v62, v55
	v_add_f32_e32 v53, v55, v53
	v_mul_f32_e32 v62, 0x3f317218, v52
	v_add_f32_e32 v55, v54, v53
	v_fma_f32 v63, v52, s13, -v62
	v_mul_f32_e32 v60, v55, v55
	v_fmac_f32_e32 v63, 0xb102e308, v52
	v_sub_f32_e32 v52, v55, v54
	v_fmamk_f32 v61, v60, 0x3e9b6dac, v160
	v_sub_f32_e32 v52, v53, v52
	v_add_f32_e32 v53, v62, v63
	v_fmaak_f32 v61, v60, v61, 0x3f2aaada
	v_sub_f32_e32 v54, v53, v62
	v_ldexp_f32 v62, v55, 1
	v_mul_f32_e32 v55, v55, v60
	v_mul_f32_e32 v55, v55, v61
	v_add_f32_e32 v60, v62, v55
	v_sub_f32_e32 v61, v60, v62
	v_ldexp_f32 v52, v52, 1
	v_sub_f32_e32 v55, v55, v61
	v_add_f32_e32 v52, v52, v55
	v_add_f32_e32 v55, v60, v52
	v_sub_f32_e32 v60, v55, v60
	v_sub_f32_e32 v52, v52, v60
	v_add_f32_e32 v60, v53, v55
	v_sub_f32_e32 v61, v60, v53
	v_sub_f32_e32 v62, v60, v61
	v_sub_f32_e32 v54, v63, v54
	v_sub_f32_e32 v53, v53, v62
	v_sub_f32_e32 v55, v55, v61
	v_add_f32_e32 v53, v55, v53
	v_add_f32_e32 v55, v54, v52
	v_sub_f32_e32 v61, v55, v54
	v_sub_f32_e32 v62, v55, v61
	v_sub_f32_e32 v54, v54, v62
	v_sub_f32_e32 v52, v52, v61
	v_add_f32_e32 v53, v55, v53
	v_add_f32_e32 v52, v52, v54
	v_add_f32_e32 v54, v60, v53
	v_sub_f32_e32 v55, v54, v60
	v_sub_f32_e32 v53, v53, v55
	v_add_f32_e32 v52, v52, v53
	v_add_f32_e32 v53, v92, v56
	v_mul_f32_e32 v53, 0xbfb8aa3b, v53
	v_exp_f32_e32 v53, v53
	v_add_f32_e32 v52, v54, v52
	v_cmp_neq_f32_e32 vcc, s14, v76
	v_exp_f32_e32 v48, v48
	v_add_f32_e32 v53, 1.0, v53
	v_rcp_f32_e32 v53, v53
	v_cndmask_b32_e32 v52, v177, v52, vcc
	v_cmp_ngt_f32_e32 vcc, -1.0, v76
	v_add_f32_e32 v48, 1.0, v48
	v_mul_f32_e32 v53, 0xc1000000, v53
	v_cndmask_b32_e32 v52, v178, v52, vcc
	v_cmp_neq_f32_e32 vcc, -1.0, v76
	v_rcp_f32_e32 v60, v48
	v_lshl_or_b32 v55, v73, 2, s10
	v_cndmask_b32_e32 v52, v179, v52, vcc
	v_cmp_lt_f32_e64 vcc, |v76|, s15
	v_add_f32_e32 v57, v92, v57
	v_mul_f32_e32 v57, 0xbfb8aa3b, v57
	v_cndmask_b32_e32 v52, v52, v76, vcc
	v_mul_f32_e32 v53, v52, v53
	v_add_f32_e32 v54, v53, v53
	v_mul_f32_e32 v54, 0x3fb8aa3b, v54
	v_exp_f32_e32 v54, v54
	v_mul_f32_e32 v48, 0x3fb8aa3b, v53
	v_exp_f32_e32 v53, v48
	v_exp_f32_e32 v57, v57
	v_sub_f32_e32 v54, 1.0, v54
	v_mul_f32_e32 v56, 0x4f800000, v54
	v_cmp_gt_f32_e32 vcc, s16, v54
	v_add_f32_e32 v49, v93, v49
	v_mul_f32_e32 v49, 0xbfb8aa3b, v49
	v_cndmask_b32_e32 v54, v54, v56, vcc
	v_sqrt_f32_e32 v56, v54
	v_exp_f32_e32 v49, v49
	v_add_f32_e32 v50, v93, v50
	v_mul_f32_e32 v50, 0xbfb8aa3b, v50
	v_add_u32_e32 v48, -1, v56
	v_fma_f32 v61, -v48, v56, v54
	v_cmp_ge_f32_e64 s[0:1], 0, v61
	v_add_u32_e32 v61, 1, v56
	v_add_f32_e32 v49, 1.0, v49
	v_cndmask_b32_e64 v48, v56, v48, s[0:1]
	v_fma_f32 v56, -v61, v56, v54
	v_cmp_lt_f32_e64 s[0:1], 0, v56
	v_exp_f32_e32 v50, v50
	v_add_f32_e32 v51, v93, v51
	v_cndmask_b32_e64 v56, v48, v61, s[0:1]
	v_lshlrev_b32_e32 v61, 2, v74
	v_lshl_or_b32 v48, v55, 8, v61
	v_add_u32_e32 v48, 0x80, v48
	ds_read_b32 v62, v48 offset:17152
	v_mul_f32_e32 v63, 0x37800000, v56
	v_cndmask_b32_e32 v56, v56, v63, vcc
	v_cmp_class_f32_e32 vcc, v54, v161
	v_add_f32_e32 v50, 1.0, v50
	v_mul_f32_e32 v51, 0xbfb8aa3b, v51
	v_cndmask_b32_e32 v54, v56, v54, vcc
	s_waitcnt lgkmcnt(0)
; #define MFMA16(a, b, c) __builtin_amdgcn_mfma_f32_16x16x32_bf16((a), (b), (c), 0, 0, 0)
; DI float sigm(float x) { return __builtin_amdgcn_rcpf(1.f + __expf(-x)); }
; DI void lru_tile(const Params& p, int layer, int isP, int sq, int tile, int nb, int pass, char*) {
;     ...
;     for (int nt = 0; nt < 4; ++nt) {
;       const int d = nt * 16 + fr;
;       const bf16x8 ba0 = wfa0[nt], ba1 = wfa1[nt], bx0 = wfx0[nt], bx1 = wfx1[nt];
;       f32x4 ar = {0.f, 0.f, 0.f, 0.f}, ai = {0.f, 0.f, 0.f, 0.f};
;       ar = MFMA16(af0, ba0, ar); ar = MFMA16(af1, ba1, ar);
;       ai = MFMA16(af0, bx0, ai); ai = MFMA16(af1, bx1, ai);
;       const float bav = pbav[nt], bxv = pbxv[nt];
;       const float sp = log1pf(__expf(-plam[nt]));
; #pragma unroll
;       for (int j = 0; j < 4; ++j) {
;         const int t = wid * 16 + fq * 4 + j;
;         float r = sigm(ar[j] + bav), ig = sigm(ai[j] + bxv);
;         float la = -8.f * r * sp;
;         float a = __expf(la);
;         float b = sqrtf(1.f - __expf(2.f * la)) * (ig * xcs[t * 64 + d]);
;         if (t0 + t >= T) { a = 1.f; b = 0.f; }
;         as_[t * 64 + d] = a;
;         bs_[t * 64 + d] = b;
;       }
;     }
	v_mul_f32_e32 v56, v62, v60
	v_mul_f32_e32 v54, v56, v54
	v_add_u32_e32 v56, s44, v55
	v_cmp_gt_i32_e32 vcc, s92, v56
	v_rcp_f32_e32 v60, v49
	v_exp_f32_e32 v51, v51
	v_cndmask_b32_e32 v53, 1.0, v53, vcc
	ds_write_b32 v48, v53
	v_add_f32_e32 v53, 1.0, v57
	v_rcp_f32_e32 v53, v53
	v_cndmask_b32_e32 v54, 0, v54, vcc
	ds_write_b32 v48, v54 offset:33536
	v_or_b32_e32 v54, 1, v55
	v_mul_f32_e32 v53, 0xc1000000, v53
	v_mul_f32_e32 v53, v52, v53
	v_add_f32_e32 v56, v53, v53
	v_mul_f32_e32 v56, 0x3fb8aa3b, v56
	v_exp_f32_e32 v56, v56
	v_mul_f32_e32 v49, 0x3fb8aa3b, v53
	v_exp_f32_e32 v53, v49
	v_mfma_f32_16x16x32_bf16 v[44:47], v[68:71], v[44:47], 0
	v_sub_f32_e32 v56, 1.0, v56
	v_mul_f32_e32 v57, 0x4f800000, v56
	v_cmp_gt_f32_e64 s[0:1], s16, v56
	v_add_f32_e32 v51, 1.0, v51
	v_mfma_f32_16x16x32_bf16 v[40:43], v[64:67], v[40:43], v[44:47]
	v_cndmask_b32_e64 v56, v56, v57, s[0:1]
	v_sqrt_f32_e32 v57, v56
	s_nop 0
	v_mul_f32_e32 v46, 0xbfb8aa3b, v94
	v_mfma_f32_16x16x32_bf16 v[36:39], v[68:71], v[36:39], 0
	v_add_u32_e32 v49, -1, v57
	v_fma_f32 v62, -v49, v57, v56
	v_cmp_ge_f32_e64 s[2:3], 0, v62
	v_add_u32_e32 v62, 1, v57
	v_exp_f32_e32 v46, v46
	v_cndmask_b32_e64 v49, v57, v49, s[2:3]
	v_fma_f32 v57, -v62, v57, v56
	v_cmp_lt_f32_e64 s[2:3], 0, v57
	v_mfma_f32_16x16x32_bf16 v[32:35], v[64:67], v[32:35], v[36:39]
	s_nop 0
	v_cndmask_b32_e64 v57, v49, v62, s[2:3]
	v_lshl_or_b32 v49, v54, 8, v61
	v_add_u32_e32 v49, 0x80, v49
	ds_read_b32 v62, v49 offset:17152
	v_mul_f32_e32 v63, 0x37800000, v57
	v_cndmask_b32_e64 v57, v57, v63, s[0:1]
	v_cmp_class_f32_e64 s[0:1], v56, v161
	v_add_u32_e32 v54, s44, v54
	v_add_f32_e32 v38, 1.0, v46
	v_cndmask_b32_e64 v56, v57, v56, s[0:1]
	s_waitcnt lgkmcnt(0)
	v_mul_f32_e32 v57, v62, v60
	v_mul_f32_e32 v56, v57, v56
	v_add_f32_e32 v57, v92, v58
	v_mul_f32_e32 v57, 0xbfb8aa3b, v57
	v_exp_f32_e32 v57, v57
	v_cmp_gt_i32_e64 s[0:1], s92, v54
	v_rcp_f32_e32 v58, v50
	v_add_f32_e32 v36, -1.0, v38
	v_cndmask_b32_e64 v53, 1.0, v53, s[0:1]
	ds_write_b32 v49, v53
	v_add_f32_e32 v53, 1.0, v57
	v_rcp_f32_e32 v53, v53
	v_cndmask_b32_e64 v54, 0, v56, s[0:1]
	ds_write_b32 v49, v54 offset:33536
	v_or_b32_e32 v54, 2, v55
	v_mul_f32_e32 v53, 0xc1000000, v53
	v_mul_f32_e32 v53, v52, v53
	v_add_f32_e32 v56, v53, v53
	v_mul_f32_e32 v56, 0x3fb8aa3b, v56
	v_exp_f32_e32 v56, v56
	v_mul_f32_e32 v50, 0x3fb8aa3b, v53
	v_exp_f32_e32 v53, v50
	v_sub_f32_e32 v37, v36, v38
	v_sub_f32_e32 v56, 1.0, v56
	v_mul_f32_e32 v57, 0x4f800000, v56
	v_cmp_gt_f32_e64 s[2:3], s16, v56
	v_add_f32_e32 v37, 1.0, v37
	v_sub_f32_e32 v36, v46, v36
	v_cndmask_b32_e64 v56, v56, v57, s[2:3]
	v_sqrt_f32_e32 v57, v56
	v_add_f32_e32 v39, v36, v37
	v_frexp_mant_f32_e32 v47, v38
	v_cvt_f64_f32_e32 v[36:37], v38
	v_add_u32_e32 v50, -1, v57
	v_fma_f32 v60, -v50, v57, v56
	v_cmp_ge_f32_e64 s[4:5], 0, v60
	v_add_u32_e32 v60, 1, v57
	v_frexp_exp_i32_f64_e32 v36, v[36:37]
	v_cndmask_b32_e64 v50, v57, v50, s[4:5]
	v_fma_f32 v57, -v60, v57, v56
	v_cmp_lt_f32_e64 s[4:5], 0, v57
	v_add_f32_e32 v32, v90, v32
	v_mul_f32_e32 v32, 0xbfb8aa3b, v32
	v_cndmask_b32_e64 v57, v50, v60, s[4:5]
	v_lshl_or_b32 v50, v54, 8, v61
	v_add_u32_e32 v50, 0x80, v50
	ds_read_b32 v60, v50 offset:17152
	v_mul_f32_e32 v62, 0x37800000, v57
	v_cndmask_b32_e64 v57, v57, v62, s[2:3]
	v_cmp_class_f32_e64 s[2:3], v56, v161
	v_add_u32_e32 v54, s44, v54
	v_exp_f32_e32 v32, v32
	v_cndmask_b32_e64 v56, v57, v56, s[2:3]
	s_waitcnt lgkmcnt(0)
	v_mul_f32_e32 v57, v58, v60
	v_mul_f32_e32 v56, v57, v56
	v_add_f32_e32 v57, v92, v59
	v_mul_f32_e32 v57, 0xbfb8aa3b, v57
	v_exp_f32_e32 v57, v57
	v_cmp_gt_i32_e64 s[2:3], s92, v54
	v_add_f32_e32 v32, 1.0, v32
	v_rcp_f32_e32 v32, v32
	v_cndmask_b32_e64 v53, 1.0, v53, s[2:3]
	ds_write_b32 v50, v53
	v_add_f32_e32 v53, 1.0, v57
	v_rcp_f32_e32 v53, v53
	v_cndmask_b32_e64 v54, 0, v56, s[2:3]
	ds_write_b32 v50, v54 offset:33536
	v_or_b32_e32 v54, 3, v55
	v_mul_f32_e32 v53, 0xc1000000, v53
	v_mul_f32_e32 v52, v52, v53
	v_add_f32_e32 v53, v52, v52
	v_mul_f32_e32 v53, 0x3fb8aa3b, v53
	v_exp_f32_e32 v53, v53
	v_rcp_f32_e32 v56, v51
	v_mul_f32_e32 v51, 0x3fb8aa3b, v52
	v_exp_f32_e32 v52, v51
	v_sub_f32_e32 v53, 1.0, v53
	v_mul_f32_e32 v55, 0x4f800000, v53
	v_cmp_gt_f32_e64 s[4:5], s16, v53
	v_add_u32_e32 v45, s44, v54
	v_add_f32_e32 v33, v90, v33
	v_cndmask_b32_e64 v53, v53, v55, s[4:5]
	v_sqrt_f32_e32 v55, v53
	v_mul_f32_e32 v33, 0xbfb8aa3b, v33
	v_exp_f32_e32 v33, v33
	v_add_f32_e32 v34, v90, v34
	v_add_u32_e32 v51, -1, v55
	v_fma_f32 v57, -v51, v55, v53
	v_cmp_ge_f32_e64 s[6:7], 0, v57
	v_add_u32_e32 v57, 1, v55
	v_mul_f32_e32 v34, 0xbfb8aa3b, v34
	v_cndmask_b32_e64 v51, v55, v51, s[6:7]
	v_fma_f32 v55, -v57, v55, v53
	v_cmp_lt_f32_e64 s[6:7], 0, v55
	v_exp_f32_e32 v34, v34
	v_add_f32_e32 v35, v90, v35
	v_cndmask_b32_e64 v55, v51, v57, s[6:7]
	v_lshl_or_b32 v51, v54, 8, v61
	v_add_u32_e32 v51, 0x80, v51
	ds_read_b32 v58, v51 offset:17152
	v_cmp_gt_f32_e64 s[6:7], s12, v47
	v_mul_f32_e32 v57, 0x37800000, v55
	v_cndmask_b32_e64 v55, v55, v57, s[4:5]
	v_subbrev_co_u32_e64 v36, s[6:7], 0, v36, s[6:7]
	v_cmp_class_f32_e64 s[4:5], v53, v161
	v_sub_u32_e32 v37, 0, v36
	s_waitcnt lgkmcnt(0)
; #define MFMA16(a, b, c) __builtin_amdgcn_mfma_f32_16x16x32_bf16((a), (b), (c), 0, 0, 0)
; DI float sigm(float x) { return __builtin_amdgcn_rcpf(1.f + __expf(-x)); }
; DI void lru_tile(const Params& p, int layer, int isP, int sq, int tile, int nb, int pass, char*) {
;     ...
;     for (int nt = 0; nt < 4; ++nt) {
;       const int d = nt * 16 + fr;
;       const bf16x8 ba0 = wfa0[nt], ba1 = wfa1[nt], bx0 = wfx0[nt], bx1 = wfx1[nt];
;       f32x4 ar = {0.f, 0.f, 0.f, 0.f}, ai = {0.f, 0.f, 0.f, 0.f};
;       ar = MFMA16(af0, ba0, ar); ar = MFMA16(af1, ba1, ar);
;       ai = MFMA16(af0, bx0, ai); ai = MFMA16(af1, bx1, ai);
;       const float bav = pbav[nt], bxv = pbxv[nt];
;       const float sp = log1pf(__expf(-plam[nt]));
; #pragma unroll
;       for (int j = 0; j < 4; ++j) {
;         const int t = wid * 16 + fq * 4 + j;
;         float r = sigm(ar[j] + bav), ig = sigm(ai[j] + bxv);
;         float la = -8.f * r * sp;
;         float a = __expf(la);
;         float b = sqrtf(1.f - __expf(2.f * la)) * (ig * xcs[t * 64 + d]);
;         if (t0 + t >= T) { a = 1.f; b = 0.f; }
;         as_[t * 64 + d] = a;
;         bs_[t * 64 + d] = b;
;       }
;     }
	v_mul_f32_e32 v44, v56, v58
	v_cndmask_b32_e64 v53, v55, v53, s[4:5]
	v_ldexp_f32 v38, v38, v37
	v_mul_f32_e32 v44, v53, v44
	v_ldexp_f32 v37, v39, v37
	v_add_f32_e32 v39, -1.0, v38
	v_add_f32_e32 v53, 1.0, v38
	v_add_f32_e32 v47, 1.0, v39
	v_add_f32_e32 v54, -1.0, v53
	v_sub_f32_e32 v47, v38, v47
	v_sub_f32_e32 v38, v38, v54
	v_add_f32_e32 v47, v37, v47
	v_add_f32_e32 v37, v37, v38
	v_add_f32_e32 v38, v53, v37
	v_cmp_gt_i32_e64 s[4:5], s92, v45
	v_rcp_f32_e32 v54, v38
	v_cvt_f32_i32_e32 v36, v36
	v_cndmask_b32_e64 v45, 1.0, v52, s[4:5]
	v_add_f32_e32 v52, v39, v47
	v_sub_f32_e32 v39, v52, v39
	v_sub_f32_e32 v39, v47, v39
	v_sub_f32_e32 v47, v38, v53
	v_sub_f32_e32 v37, v37, v47
	v_mul_f32_e32 v47, v52, v54
	v_mul_f32_e32 v53, v38, v47
	v_fma_f32 v55, v47, v38, -v53
	v_fmac_f32_e32 v55, v47, v37
	v_add_f32_e32 v56, v53, v55
	v_sub_f32_e32 v57, v52, v56
	v_sub_f32_e32 v52, v52, v57
	v_sub_f32_e32 v53, v56, v53
	v_sub_f32_e32 v52, v52, v56
	v_add_f32_e32 v39, v39, v52
	v_sub_f32_e32 v52, v53, v55
	v_add_f32_e32 v39, v52, v39
	v_add_f32_e32 v52, v57, v39
	v_mul_f32_e32 v53, v54, v52
	v_mul_f32_e32 v55, v38, v53
	v_fma_f32 v38, v53, v38, -v55
	v_fmac_f32_e32 v38, v53, v37
	v_sub_f32_e32 v37, v57, v52
	v_add_f32_e32 v37, v39, v37
	v_add_f32_e32 v39, v55, v38
	v_sub_f32_e32 v56, v52, v39
	v_sub_f32_e32 v52, v52, v56
	v_sub_f32_e32 v55, v39, v55
	v_sub_f32_e32 v39, v52, v39
	v_add_f32_e32 v37, v37, v39
	v_sub_f32_e32 v38, v55, v38
	v_add_f32_e32 v37, v38, v37
	v_add_f32_e32 v38, v47, v53
	v_add_f32_e32 v37, v56, v37
	v_sub_f32_e32 v39, v38, v47
	v_mul_f32_e32 v37, v54, v37
	v_sub_f32_e32 v39, v53, v39
	v_add_f32_e32 v37, v39, v37
	v_mul_f32_e32 v53, 0x3f317218, v36
	v_add_f32_e32 v39, v38, v37
	v_fma_f32 v54, v36, s13, -v53
	v_mul_f32_e32 v47, v39, v39
	v_fmac_f32_e32 v54, 0xb102e308, v36
	v_sub_f32_e32 v36, v39, v38
	v_fmamk_f32 v52, v47, 0x3e9b6dac, v160
	v_sub_f32_e32 v36, v37, v36
	v_add_f32_e32 v37, v53, v54
	v_fmaak_f32 v52, v47, v52, 0x3f2aaada
	v_sub_f32_e32 v38, v37, v53
	v_ldexp_f32 v53, v39, 1
	v_mul_f32_e32 v39, v39, v47
	v_mul_f32_e32 v39, v39, v52
	v_add_f32_e32 v47, v53, v39
	v_sub_f32_e32 v52, v47, v53
	v_ldexp_f32 v36, v36, 1
	v_sub_f32_e32 v39, v39, v52
	v_add_f32_e32 v36, v36, v39
	v_add_f32_e32 v39, v47, v36
	v_sub_f32_e32 v47, v39, v47
	v_sub_f32_e32 v36, v36, v47
	v_add_f32_e32 v47, v37, v39
	v_sub_f32_e32 v52, v47, v37
	v_sub_f32_e32 v53, v47, v52
	v_sub_f32_e32 v38, v54, v38
	v_sub_f32_e32 v37, v37, v53
	v_sub_f32_e32 v39, v39, v52
	v_add_f32_e32 v37, v39, v37
	v_add_f32_e32 v39, v38, v36
	v_sub_f32_e32 v52, v39, v38
	v_sub_f32_e32 v53, v39, v52
	v_sub_f32_e32 v38, v38, v53
	v_sub_f32_e32 v36, v36, v52
	v_add_f32_e32 v37, v39, v37
	v_add_f32_e32 v36, v36, v38
	v_add_f32_e32 v38, v47, v37
	v_sub_f32_e32 v39, v38, v47
	v_sub_f32_e32 v37, v37, v39
	v_add_f32_e32 v36, v36, v37
	v_add_f32_e32 v37, v91, v40
	v_mul_f32_e32 v37, 0xbfb8aa3b, v37
	v_exp_f32_e32 v37, v37
	v_add_f32_e32 v36, v38, v36
	v_cmp_neq_f32_e64 s[6:7], s14, v46
	v_cndmask_b32_e64 v44, 0, v44, s[4:5]
	v_add_f32_e32 v37, 1.0, v37
	v_rcp_f32_e32 v37, v37
	v_cndmask_b32_e64 v36, v177, v36, s[6:7]
	v_cmp_ngt_f32_e64 s[6:7], -1.0, v46
	ds_write_b32 v51, v45
	ds_write_b32 v51, v44 offset:33536
	v_cndmask_b32_e64 v36, v178, v36, s[6:7]
	v_cmp_neq_f32_e64 s[6:7], -1.0, v46
	v_mul_f32_e32 v37, 0xc1000000, v37
	v_mul_f32_e32 v35, 0xbfb8aa3b, v35
	v_cndmask_b32_e64 v36, v179, v36, s[6:7]
	v_cmp_lt_f32_e64 s[6:7], |v46|, s15
	v_exp_f32_e32 v35, v35
	v_mfma_f32_16x16x32_bf16 v[28:31], v[68:71], v[28:31], 0
	v_cndmask_b32_e64 v36, v36, v46, s[6:7]
	v_mul_f32_e32 v37, v36, v37
	v_add_f32_e32 v38, v37, v37
	v_mul_f32_e32 v38, 0x3fb8aa3b, v38
	v_exp_f32_e32 v38, v38
	v_mul_f32_e32 v37, 0x3fb8aa3b, v37
	v_exp_f32_e32 v37, v37
	v_mfma_f32_16x16x32_bf16 v[24:27], v[64:67], v[24:27], v[28:31]
	v_sub_f32_e32 v38, 1.0, v38
	v_mul_f32_e32 v39, 0x4f800000, v38
	v_cmp_gt_f32_e64 s[6:7], s16, v38
	v_cndmask_b32_e32 v37, 1.0, v37, vcc
	v_mfma_f32_16x16x32_bf16 v[20:23], v[68:71], v[20:23], 0
	v_cndmask_b32_e64 v38, v38, v39, s[6:7]
	v_sqrt_f32_e32 v39, v38
	v_mfma_f32_16x16x32_bf16 v[16:19], v[64:67], v[16:19], v[20:23]
	v_add_u32_e32 v40, -1, v39
	v_fma_f32 v44, -v40, v39, v38
	v_cmp_ge_f32_e64 s[8:9], 0, v44
	v_add_u32_e32 v44, 1, v39
	s_nop 3
	v_add_f32_e32 v16, v87, v16
	v_cndmask_b32_e64 v40, v39, v40, s[8:9]
	v_fma_f32 v39, -v44, v39, v38
	v_cmp_lt_f32_e64 s[8:9], 0, v39
	v_mul_f32_e32 v16, 0xbfb8aa3b, v16
	v_exp_f32_e32 v16, v16
	v_cndmask_b32_e64 v39, v40, v44, s[8:9]
	v_mul_f32_e32 v44, 0x37800000, v39
	v_cndmask_b32_e64 v39, v39, v44, s[6:7]
	v_cmp_class_f32_e64 s[6:7], v38, v161
	ds_read_b32 v40, v48 offset:17216
	v_add_f32_e32 v16, 1.0, v16
	v_cndmask_b32_e64 v38, v39, v38, s[6:7]
	v_add_f32_e32 v39, v91, v41
	v_mul_f32_e32 v39, 0xbfb8aa3b, v39
	v_exp_f32_e32 v39, v39
	s_waitcnt lgkmcnt(0)
	v_mul_f32_e32 v32, v40, v32
	v_mul_f32_e32 v32, v32, v38
	v_cndmask_b32_e32 v32, 0, v32, vcc
	v_add_f32_e32 v38, 1.0, v39
	v_rcp_f32_e32 v38, v38
	ds_write_b32 v48, v37 offset:64
	ds_write_b32 v48, v32 offset:33600
	v_add_f32_e32 v32, 1.0, v33
	v_rcp_f32_e32 v32, v32
	v_mul_f32_e32 v38, 0xc1000000, v38
	v_mul_f32_e32 v38, v36, v38
	v_add_f32_e32 v39, v38, v38
	v_mul_f32_e32 v39, 0x3fb8aa3b, v39
	v_exp_f32_e32 v39, v39
	v_mul_f32_e32 v38, 0x3fb8aa3b, v38
	v_exp_f32_e32 v38, v38
	v_rcp_f32_e32 v16, v16
	v_sub_f32_e32 v33, 1.0, v39
	v_mul_f32_e32 v37, 0x4f800000, v33
	v_cmp_gt_f32_e64 s[6:7], s16, v33
	v_add_f32_e32 v17, v87, v17
	v_mul_f32_e32 v17, 0xbfb8aa3b, v17
	v_cndmask_b32_e64 v33, v33, v37, s[6:7]
	v_sqrt_f32_e32 v37, v33
	v_exp_f32_e32 v17, v17
	v_add_f32_e32 v18, v87, v18
	v_mul_f32_e32 v18, 0xbfb8aa3b, v18
	v_add_u32_e32 v39, -1, v37
	v_fma_f32 v40, -v39, v37, v33
	v_cmp_ge_f32_e64 s[8:9], 0, v40
	v_add_u32_e32 v40, 1, v37
	v_exp_f32_e32 v18, v18
	v_cndmask_b32_e64 v39, v37, v39, s[8:9]
	v_fma_f32 v37, -v40, v37, v33
	v_cmp_lt_f32_e64 s[8:9], 0, v37
	v_add_f32_e32 v19, v87, v19
	v_mul_f32_e32 v19, 0xbfb8aa3b, v19
	v_cndmask_b32_e64 v37, v39, v40, s[8:9]
	v_mul_f32_e32 v40, 0x37800000, v37
	v_cndmask_b32_e64 v37, v37, v40, s[6:7]
	v_cmp_class_f32_e64 s[6:7], v33, v161
	ds_read_b32 v39, v49 offset:17216
	v_exp_f32_e32 v19, v19
	v_cndmask_b32_e64 v33, v37, v33, s[6:7]
	v_add_f32_e32 v37, v91, v42
	v_mul_f32_e32 v37, 0xbfb8aa3b, v37
	v_exp_f32_e32 v37, v37
	s_waitcnt lgkmcnt(0)
; #define MFMA16(a, b, c) __builtin_amdgcn_mfma_f32_16x16x32_bf16((a), (b), (c), 0, 0, 0)
; DI float sigm(float x) { return __builtin_amdgcn_rcpf(1.f + __expf(-x)); }
; DI void lru_tile(const Params& p, int layer, int isP, int sq, int tile, int nb, int pass, char*) {
;     ...
;     for (int nt = 0; nt < 4; ++nt) {
;       const int d = nt * 16 + fr;
;       const bf16x8 ba0 = wfa0[nt], ba1 = wfa1[nt], bx0 = wfx0[nt], bx1 = wfx1[nt];
;       f32x4 ar = {0.f, 0.f, 0.f, 0.f}, ai = {0.f, 0.f, 0.f, 0.f};
;       ar = MFMA16(af0, ba0, ar); ar = MFMA16(af1, ba1, ar);
;       ai = MFMA16(af0, bx0, ai); ai = MFMA16(af1, bx1, ai);
;       const float bav = pbav[nt], bxv = pbxv[nt];
;       const float sp = log1pf(__expf(-plam[nt]));
; #pragma unroll
;       for (int j = 0; j < 4; ++j) {
;         const int t = wid * 16 + fq * 4 + j;
;         float r = sigm(ar[j] + bav), ig = sigm(ai[j] + bxv);
;         float la = -8.f * r * sp;
;         float a = __expf(la);
;         float b = sqrtf(1.f - __expf(2.f * la)) * (ig * xcs[t * 64 + d]);
;         if (t0 + t >= T) { a = 1.f; b = 0.f; }
;         as_[t * 64 + d] = a;
;         bs_[t * 64 + d] = b;
;       }
;     }
	v_mul_f32_e32 v32, v39, v32
	v_mul_f32_e32 v32, v32, v33
	v_cndmask_b32_e64 v33, 1.0, v38, s[0:1]
	v_add_f32_e32 v37, 1.0, v37
	v_rcp_f32_e32 v37, v37
	v_cndmask_b32_e64 v32, 0, v32, s[0:1]
	ds_write_b32 v49, v33 offset:64
	ds_write_b32 v49, v32 offset:33600
	v_add_f32_e32 v32, 1.0, v34
	v_mul_f32_e32 v37, 0xc1000000, v37
	v_mul_f32_e32 v37, v36, v37
	v_add_f32_e32 v38, v37, v37
	v_mul_f32_e32 v38, 0x3fb8aa3b, v38
	v_exp_f32_e32 v38, v38
	v_rcp_f32_e32 v32, v32
	v_mul_f32_e32 v37, 0x3fb8aa3b, v37
	v_exp_f32_e32 v37, v37
	v_sub_f32_e32 v33, 1.0, v38
	v_mul_f32_e32 v34, 0x4f800000, v33
	v_cmp_gt_f32_e64 s[6:7], s16, v33
	v_mfma_f32_16x16x32_bf16 v[12:15], v[68:71], v[12:15], 0
	s_nop 0
	v_cndmask_b32_e64 v33, v33, v34, s[6:7]
	v_sqrt_f32_e32 v34, v33
	v_mfma_f32_16x16x32_bf16 v[8:11], v[64:67], v[8:11], v[12:15]
	v_add_u32_e32 v38, -1, v34
	v_fma_f32 v39, -v38, v34, v33
	v_cmp_ge_f32_e64 s[8:9], 0, v39
	v_add_u32_e32 v39, 1, v34
	v_mfma_f32_16x16x32_bf16 v[4:7], v[68:71], v[4:7], 0
	v_cndmask_b32_e64 v38, v34, v38, s[8:9]
	v_fma_f32 v34, -v39, v34, v33
	v_cmp_lt_f32_e64 s[8:9], 0, v34
	v_mfma_f32_16x16x32_bf16 v[0:3], v[64:67], v[0:3], v[4:7]
	s_nop 0
	v_cndmask_b32_e64 v34, v38, v39, s[8:9]
	v_mul_f32_e32 v39, 0x37800000, v34
	v_cndmask_b32_e64 v34, v34, v39, s[6:7]
	v_cmp_class_f32_e64 s[6:7], v33, v161
	ds_read_b32 v38, v50 offset:17216
	s_nop 1
	v_add_f32_e32 v0, v84, v0
	v_cndmask_b32_e64 v33, v34, v33, s[6:7]
	v_add_f32_e32 v34, v91, v43
	v_mul_f32_e32 v34, 0xbfb8aa3b, v34
	v_exp_f32_e32 v34, v34
	s_waitcnt lgkmcnt(0)
	v_mul_f32_e32 v32, v32, v38
	v_mul_f32_e32 v32, v32, v33
	v_cndmask_b32_e64 v33, 1.0, v37, s[2:3]
	v_add_f32_e32 v34, 1.0, v34
	v_rcp_f32_e32 v34, v34
	v_cndmask_b32_e64 v32, 0, v32, s[2:3]
	ds_write_b32 v50, v33 offset:64
	ds_write_b32 v50, v32 offset:33600
	v_add_f32_e32 v32, 1.0, v35
	v_mul_f32_e32 v34, 0xc1000000, v34
	v_mul_f32_e32 v34, v36, v34
	v_add_f32_e32 v36, v34, v34
	v_mul_f32_e32 v36, 0x3fb8aa3b, v36
	v_exp_f32_e32 v36, v36
	v_rcp_f32_e32 v32, v32
	v_mul_f32_e32 v34, 0x3fb8aa3b, v34
	v_exp_f32_e32 v34, v34
	v_sub_f32_e32 v33, 1.0, v36
	v_mul_f32_e32 v35, 0x4f800000, v33
	v_cmp_gt_f32_e64 s[6:7], s16, v33
	v_cndmask_b32_e64 v30, 1.0, v34, s[4:5]
	v_mul_f32_e32 v0, 0xbfb8aa3b, v0
	v_cndmask_b32_e64 v33, v33, v35, s[6:7]
	v_sqrt_f32_e32 v35, v33
	v_exp_f32_e32 v0, v0
	v_add_f32_e32 v1, v84, v1
	v_mul_f32_e32 v1, 0xbfb8aa3b, v1
	v_add_u32_e32 v36, -1, v35
	v_fma_f32 v37, -v36, v35, v33
	v_cmp_ge_f32_e64 s[8:9], 0, v37
	v_add_u32_e32 v37, 1, v35
	v_add_f32_e32 v0, 1.0, v0
	v_cndmask_b32_e64 v36, v35, v36, s[8:9]
	v_fma_f32 v35, -v37, v35, v33
	v_cmp_lt_f32_e64 s[8:9], 0, v35
	v_rcp_f32_e32 v0, v0
	v_exp_f32_e32 v1, v1
	v_cndmask_b32_e64 v35, v36, v37, s[8:9]
	ds_read_b32 v37, v51 offset:17216
	v_mul_f32_e32 v36, 0x37800000, v35
	v_cndmask_b32_e64 v35, v35, v36, s[6:7]
	v_cmp_class_f32_e64 s[6:7], v33, v161
	v_add_f32_e32 v2, v84, v2
	s_waitcnt lgkmcnt(0)
	v_mul_f32_e32 v29, v32, v37
	v_cndmask_b32_e64 v28, v35, v33, s[6:7]
	v_mul_f32_e32 v28, v28, v29
	v_mul_f32_e32 v29, 0xbfb8aa3b, v89
	v_exp_f32_e32 v29, v29
	v_cndmask_b32_e64 v28, 0, v28, s[4:5]
	ds_write_b32 v51, v30 offset:64
	ds_write_b32 v51, v28 offset:33600
	v_mul_f32_e32 v2, 0xbfb8aa3b, v2
	v_add_f32_e32 v22, 1.0, v29
	v_add_f32_e32 v20, -1.0, v22
	v_sub_f32_e32 v21, v20, v22
	v_add_f32_e32 v21, 1.0, v21
	v_sub_f32_e32 v20, v29, v20
	v_add_f32_e32 v23, v20, v21
	v_frexp_mant_f32_e32 v31, v22
	v_cvt_f64_f32_e32 v[20:21], v22
	v_frexp_exp_i32_f64_e32 v20, v[20:21]
	v_cmp_gt_f32_e64 s[6:7], s12, v31
	v_exp_f32_e32 v2, v2
	v_add_f32_e32 v3, v84, v3
	v_subbrev_co_u32_e64 v20, s[6:7], 0, v20, s[6:7]
	v_sub_u32_e32 v21, 0, v20
	v_ldexp_f32 v22, v22, v21
	v_ldexp_f32 v21, v23, v21
	v_add_f32_e32 v23, -1.0, v22
	v_add_f32_e32 v33, 1.0, v22
	v_add_f32_e32 v31, 1.0, v23
	v_add_f32_e32 v34, -1.0, v33
	v_sub_f32_e32 v31, v22, v31
	v_sub_f32_e32 v22, v22, v34
	v_add_f32_e32 v31, v21, v31
	v_add_f32_e32 v21, v21, v22
	v_add_f32_e32 v22, v33, v21
	v_rcp_f32_e32 v34, v22
	v_add_f32_e32 v32, v23, v31
	v_sub_f32_e32 v23, v32, v23
	v_sub_f32_e32 v23, v31, v23
	v_sub_f32_e32 v31, v22, v33
	v_sub_f32_e32 v21, v21, v31
	v_mul_f32_e32 v31, v32, v34
	v_mul_f32_e32 v33, v22, v31
	v_fma_f32 v35, v31, v22, -v33
	v_fmac_f32_e32 v35, v31, v21
	v_add_f32_e32 v36, v33, v35
	v_sub_f32_e32 v37, v32, v36
	v_sub_f32_e32 v32, v32, v37
	v_sub_f32_e32 v33, v36, v33
	v_sub_f32_e32 v32, v32, v36
	v_add_f32_e32 v23, v23, v32
	v_sub_f32_e32 v32, v33, v35
	v_add_f32_e32 v23, v32, v23
	v_add_f32_e32 v32, v37, v23
	v_mul_f32_e32 v33, v34, v32
	v_mul_f32_e32 v35, v22, v33
	v_fma_f32 v22, v33, v22, -v35
	v_fmac_f32_e32 v22, v33, v21
	v_sub_f32_e32 v21, v37, v32
	v_add_f32_e32 v21, v23, v21
	v_add_f32_e32 v23, v35, v22
	v_sub_f32_e32 v36, v32, v23
	v_sub_f32_e32 v32, v32, v36
	v_sub_f32_e32 v35, v23, v35
	v_sub_f32_e32 v23, v32, v23
	v_add_f32_e32 v21, v21, v23
	v_sub_f32_e32 v22, v35, v22
	v_cvt_f32_i32_e32 v20, v20
	v_add_f32_e32 v21, v22, v21
	v_add_f32_e32 v22, v31, v33
	v_add_f32_e32 v21, v36, v21
	v_sub_f32_e32 v23, v22, v31
	v_mul_f32_e32 v21, v34, v21
	v_sub_f32_e32 v23, v33, v23
	v_add_f32_e32 v21, v23, v21
	v_mul_f32_e32 v33, 0x3f317218, v20
	v_add_f32_e32 v23, v22, v21
	v_fma_f32 v34, v20, s13, -v33
	v_mul_f32_e32 v31, v23, v23
	v_fmac_f32_e32 v34, 0xb102e308, v20
	v_sub_f32_e32 v20, v23, v22
	v_fmamk_f32 v32, v31, 0x3e9b6dac, v160
	v_sub_f32_e32 v20, v21, v20
	v_add_f32_e32 v21, v33, v34
	v_fmaak_f32 v32, v31, v32, 0x3f2aaada
	v_sub_f32_e32 v22, v21, v33
	v_ldexp_f32 v33, v23, 1
	v_mul_f32_e32 v23, v23, v31
	v_mul_f32_e32 v23, v23, v32
	v_add_f32_e32 v31, v33, v23
	v_sub_f32_e32 v32, v31, v33
; #define MFMA16(a, b, c) __builtin_amdgcn_mfma_f32_16x16x32_bf16((a), (b), (c), 0, 0, 0)
; DI float sigm(float x) { return __builtin_amdgcn_rcpf(1.f + __expf(-x)); }
; DI void lru_tile(const Params& p, int layer, int isP, int sq, int tile, int nb, int pass, char*) {
;     ...
;     for (int nt = 0; nt < 4; ++nt) {
;       const int d = nt * 16 + fr;
;       const bf16x8 ba0 = wfa0[nt], ba1 = wfa1[nt], bx0 = wfx0[nt], bx1 = wfx1[nt];
;       f32x4 ar = {0.f, 0.f, 0.f, 0.f}, ai = {0.f, 0.f, 0.f, 0.f};
;       ar = MFMA16(af0, ba0, ar); ar = MFMA16(af1, ba1, ar);
;       ai = MFMA16(af0, bx0, ai); ai = MFMA16(af1, bx1, ai);
;       const float bav = pbav[nt], bxv = pbxv[nt];
;       const float sp = log1pf(__expf(-plam[nt]));
; #pragma unroll
;       for (int j = 0; j < 4; ++j) {
;         const int t = wid * 16 + fq * 4 + j;
;         float r = sigm(ar[j] + bav), ig = sigm(ai[j] + bxv);
;         float la = -8.f * r * sp;
;         float a = __expf(la);
;         float b = sqrtf(1.f - __expf(2.f * la)) * (ig * xcs[t * 64 + d]);
;         if (t0 + t >= T) { a = 1.f; b = 0.f; }
;         as_[t * 64 + d] = a;
;         bs_[t * 64 + d] = b;
;       }
;     }
	v_ldexp_f32 v20, v20, 1
	v_sub_f32_e32 v23, v23, v32
	v_add_f32_e32 v20, v20, v23
	v_add_f32_e32 v23, v31, v20
	v_sub_f32_e32 v31, v23, v31
	v_sub_f32_e32 v20, v20, v31
	v_add_f32_e32 v31, v21, v23
	v_sub_f32_e32 v32, v31, v21
	v_sub_f32_e32 v33, v31, v32
	v_sub_f32_e32 v22, v34, v22
	v_sub_f32_e32 v21, v21, v33
	v_sub_f32_e32 v23, v23, v32
	v_add_f32_e32 v21, v23, v21
	v_add_f32_e32 v23, v22, v20
	v_sub_f32_e32 v32, v23, v22
	v_sub_f32_e32 v33, v23, v32
	v_sub_f32_e32 v22, v22, v33
	v_sub_f32_e32 v20, v20, v32
	v_add_f32_e32 v21, v23, v21
	v_add_f32_e32 v20, v20, v22
	v_add_f32_e32 v22, v31, v21
	v_sub_f32_e32 v23, v22, v31
	v_sub_f32_e32 v21, v21, v23
	v_add_f32_e32 v20, v20, v21
	v_add_f32_e32 v21, v88, v24
	v_mul_f32_e32 v21, 0xbfb8aa3b, v21
	v_exp_f32_e32 v21, v21
	v_add_f32_e32 v20, v22, v20
	v_cmp_neq_f32_e64 s[6:7], s14, v29
	v_mul_f32_e32 v3, 0xbfb8aa3b, v3
	v_add_f32_e32 v21, 1.0, v21
	v_rcp_f32_e32 v21, v21
	v_cndmask_b32_e64 v20, v177, v20, s[6:7]
	v_cmp_ngt_f32_e64 s[6:7], -1.0, v29
	v_exp_f32_e32 v3, v3
	v_mul_f32_e32 v21, 0xc1000000, v21
	v_cndmask_b32_e64 v20, v178, v20, s[6:7]
	v_cmp_neq_f32_e64 s[6:7], -1.0, v29
	s_nop 1
	v_cndmask_b32_e64 v20, v179, v20, s[6:7]
	v_cmp_lt_f32_e64 s[6:7], |v29|, s15
	s_nop 1
	v_cndmask_b32_e64 v20, v20, v29, s[6:7]
	v_mul_f32_e32 v21, v20, v21
	v_add_f32_e32 v22, v21, v21
	v_mul_f32_e32 v22, 0x3fb8aa3b, v22
	v_exp_f32_e32 v22, v22
	v_mul_f32_e32 v21, 0x3fb8aa3b, v21
	v_exp_f32_e32 v21, v21
	v_sub_f32_e32 v22, 1.0, v22
	v_mul_f32_e32 v23, 0x4f800000, v22
	v_cmp_gt_f32_e64 s[6:7], s16, v22
	v_cndmask_b32_e32 v21, 1.0, v21, vcc
	s_nop 0
	v_cndmask_b32_e64 v22, v22, v23, s[6:7]
	v_sqrt_f32_e32 v23, v22
	s_nop 0
	v_add_u32_e32 v24, -1, v23
	v_fma_f32 v28, -v24, v23, v22
	v_cmp_ge_f32_e64 s[8:9], 0, v28
	v_add_u32_e32 v28, 1, v23
	s_nop 0
	v_cndmask_b32_e64 v24, v23, v24, s[8:9]
	v_fma_f32 v23, -v28, v23, v22
	v_cmp_lt_f32_e64 s[8:9], 0, v23
	s_nop 1
	v_cndmask_b32_e64 v23, v24, v28, s[8:9]
	v_mul_f32_e32 v28, 0x37800000, v23
	v_cndmask_b32_e64 v23, v23, v28, s[6:7]
	v_cmp_class_f32_e64 s[6:7], v22, v161
	ds_read_b32 v24, v48 offset:17280
	s_waitcnt lgkmcnt(0)
	v_mul_f32_e32 v16, v24, v16
	v_cndmask_b32_e64 v22, v23, v22, s[6:7]
	v_add_f32_e32 v23, v88, v25
	v_mul_f32_e32 v23, 0xbfb8aa3b, v23
	v_exp_f32_e32 v23, v23
	v_mul_f32_e32 v16, v16, v22
	v_cndmask_b32_e32 v16, 0, v16, vcc
	ds_write_b32 v48, v21 offset:128
	ds_write_b32 v48, v16 offset:33664
	v_add_f32_e32 v22, 1.0, v23
	v_rcp_f32_e32 v22, v22
	v_add_f32_e32 v16, 1.0, v17
	v_rcp_f32_e32 v16, v16
	v_mul_f32_e32 v22, 0xc1000000, v22
	v_mul_f32_e32 v22, v20, v22
	v_add_f32_e32 v23, v22, v22
	v_mul_f32_e32 v23, 0x3fb8aa3b, v23
	v_exp_f32_e32 v23, v23
	v_mul_f32_e32 v22, 0x3fb8aa3b, v22
	v_exp_f32_e32 v22, v22
	v_sub_f32_e32 v17, 1.0, v23
	v_mul_f32_e32 v21, 0x4f800000, v17
	v_cmp_gt_f32_e64 s[6:7], s16, v17
	s_nop 1
	v_cndmask_b32_e64 v17, v17, v21, s[6:7]
	v_sqrt_f32_e32 v21, v17
	s_nop 0
	v_add_u32_e32 v23, -1, v21
	v_fma_f32 v24, -v23, v21, v17
	v_cmp_ge_f32_e64 s[8:9], 0, v24
	v_add_u32_e32 v24, 1, v21
	s_nop 0
	v_cndmask_b32_e64 v23, v21, v23, s[8:9]
	v_fma_f32 v21, -v24, v21, v17
	v_cmp_lt_f32_e64 s[8:9], 0, v21
	s_nop 1
	v_cndmask_b32_e64 v21, v23, v24, s[8:9]
	v_mul_f32_e32 v24, 0x37800000, v21
	v_cndmask_b32_e64 v21, v21, v24, s[6:7]
	v_cmp_class_f32_e64 s[6:7], v17, v161
	ds_read_b32 v23, v49 offset:17280
	s_waitcnt lgkmcnt(0)
	v_mul_f32_e32 v16, v23, v16
	v_cndmask_b32_e64 v17, v21, v17, s[6:7]
	v_add_f32_e32 v21, v88, v26
	v_mul_f32_e32 v21, 0xbfb8aa3b, v21
	v_exp_f32_e32 v21, v21
	v_mul_f32_e32 v16, v16, v17
	v_cndmask_b32_e64 v17, 1.0, v22, s[0:1]
	v_cndmask_b32_e64 v16, 0, v16, s[0:1]
	v_add_f32_e32 v21, 1.0, v21
	v_rcp_f32_e32 v21, v21
	ds_write_b32 v49, v17 offset:128
	ds_write_b32 v49, v16 offset:33664
	v_add_f32_e32 v16, 1.0, v18
	v_rcp_f32_e32 v16, v16
	v_mul_f32_e32 v21, 0xc1000000, v21
	v_mul_f32_e32 v21, v20, v21
	v_add_f32_e32 v22, v21, v21
	v_mul_f32_e32 v22, 0x3fb8aa3b, v22
	v_exp_f32_e32 v22, v22
	v_mul_f32_e32 v21, 0x3fb8aa3b, v21
	v_exp_f32_e32 v21, v21
	v_sub_f32_e32 v17, 1.0, v22
	v_mul_f32_e32 v18, 0x4f800000, v17
	v_cmp_gt_f32_e64 s[6:7], s16, v17
	s_nop 1
	v_cndmask_b32_e64 v17, v17, v18, s[6:7]
	v_sqrt_f32_e32 v18, v17
	s_nop 0
	v_add_u32_e32 v22, -1, v18
	v_fma_f32 v23, -v22, v18, v17
	v_cmp_ge_f32_e64 s[8:9], 0, v23
	v_add_u32_e32 v23, 1, v18
	s_nop 0
	v_cndmask_b32_e64 v22, v18, v22, s[8:9]
	v_fma_f32 v18, -v23, v18, v17
	v_cmp_lt_f32_e64 s[8:9], 0, v18
	s_nop 1
	v_cndmask_b32_e64 v18, v22, v23, s[8:9]
	v_mul_f32_e32 v23, 0x37800000, v18
	v_cndmask_b32_e64 v18, v18, v23, s[6:7]
	v_cmp_class_f32_e64 s[6:7], v17, v161
	ds_read_b32 v22, v50 offset:17280
	s_waitcnt lgkmcnt(0)
	v_mul_f32_e32 v16, v16, v22
	v_cndmask_b32_e64 v17, v18, v17, s[6:7]
	v_add_f32_e32 v18, v88, v27
	v_mul_f32_e32 v18, 0xbfb8aa3b, v18
	v_exp_f32_e32 v18, v18
	v_mul_f32_e32 v16, v16, v17
	v_cndmask_b32_e64 v17, 1.0, v21, s[2:3]
	v_cndmask_b32_e64 v16, 0, v16, s[2:3]
	v_add_f32_e32 v18, 1.0, v18
	v_rcp_f32_e32 v18, v18
	ds_write_b32 v50, v17 offset:128
	ds_write_b32 v50, v16 offset:33664
	v_add_f32_e32 v16, 1.0, v19
	v_rcp_f32_e32 v16, v16
	v_mul_f32_e32 v18, 0xc1000000, v18
	v_mul_f32_e32 v18, v20, v18
	v_add_f32_e32 v20, v18, v18
	v_mul_f32_e32 v20, 0x3fb8aa3b, v20
	v_exp_f32_e32 v20, v20
	v_mul_f32_e32 v18, 0x3fb8aa3b, v18
	v_exp_f32_e32 v18, v18
	v_sub_f32_e32 v17, 1.0, v20
	v_mul_f32_e32 v19, 0x4f800000, v17
	v_cmp_gt_f32_e64 s[6:7], s16, v17
	v_cndmask_b32_e64 v14, 1.0, v18, s[4:5]
	s_nop 0
	v_cndmask_b32_e64 v17, v17, v19, s[6:7]
	v_sqrt_f32_e32 v19, v17
	s_nop 0
	v_add_u32_e32 v20, -1, v19
	v_fma_f32 v21, -v20, v19, v17
	v_cmp_ge_f32_e64 s[8:9], 0, v21
	v_add_u32_e32 v21, 1, v19
	s_nop 0
	v_cndmask_b32_e64 v20, v19, v20, s[8:9]
	v_fma_f32 v19, -v21, v19, v17
	v_cmp_lt_f32_e64 s[8:9], 0, v19
	s_nop 1
	v_cndmask_b32_e64 v19, v20, v21, s[8:9]
	ds_read_b32 v21, v51 offset:17280
	v_mul_f32_e32 v20, 0x37800000, v19
	v_cndmask_b32_e64 v19, v19, v20, s[6:7]
	v_cmp_class_f32_e64 s[6:7], v17, v161
	s_waitcnt lgkmcnt(0)
; #define MFMA16(a, b, c) __builtin_amdgcn_mfma_f32_16x16x32_bf16((a), (b), (c), 0, 0, 0)
; DI float sigm(float x) { return __builtin_amdgcn_rcpf(1.f + __expf(-x)); }
; DI void lru_tile(const Params& p, int layer, int isP, int sq, int tile, int nb, int pass, char*) {
;     ...
;     for (int nt = 0; nt < 4; ++nt) {
;       const int d = nt * 16 + fr;
;       const bf16x8 ba0 = wfa0[nt], ba1 = wfa1[nt], bx0 = wfx0[nt], bx1 = wfx1[nt];
;       f32x4 ar = {0.f, 0.f, 0.f, 0.f}, ai = {0.f, 0.f, 0.f, 0.f};
;       ar = MFMA16(af0, ba0, ar); ar = MFMA16(af1, ba1, ar);
;       ai = MFMA16(af0, bx0, ai); ai = MFMA16(af1, bx1, ai);
;       const float bav = pbav[nt], bxv = pbxv[nt];
;       const float sp = log1pf(__expf(-plam[nt]));
; #pragma unroll
;       for (int j = 0; j < 4; ++j) {
;         const int t = wid * 16 + fq * 4 + j;
;         float r = sigm(ar[j] + bav), ig = sigm(ai[j] + bxv);
;         float la = -8.f * r * sp;
;         float a = __expf(la);
;         float b = sqrtf(1.f - __expf(2.f * la)) * (ig * xcs[t * 64 + d]);
;         if (t0 + t >= T) { a = 1.f; b = 0.f; }
;         as_[t * 64 + d] = a;
;         bs_[t * 64 + d] = b;
;       }
;     }
	v_mul_f32_e32 v13, v16, v21
	v_cndmask_b32_e64 v12, v19, v17, s[6:7]
	v_mul_f32_e32 v12, v12, v13
	v_mul_f32_e32 v13, 0xbfb8aa3b, v86
	v_exp_f32_e32 v13, v13
	v_cndmask_b32_e64 v12, 0, v12, s[4:5]
	ds_write_b32 v51, v14 offset:128
	ds_write_b32 v51, v12 offset:33664
	v_add_f32_e32 v6, 1.0, v13
	v_add_f32_e32 v4, -1.0, v6
	v_sub_f32_e32 v5, v4, v6
	v_add_f32_e32 v5, 1.0, v5
	v_sub_f32_e32 v4, v13, v4
	v_add_f32_e32 v7, v4, v5
	v_frexp_mant_f32_e32 v15, v6
	v_cvt_f64_f32_e32 v[4:5], v6
	v_frexp_exp_i32_f64_e32 v4, v[4:5]
	v_cmp_gt_f32_e64 s[6:7], s12, v15
	s_nop 1
	v_subbrev_co_u32_e64 v4, s[6:7], 0, v4, s[6:7]
	v_sub_u32_e32 v5, 0, v4
	v_ldexp_f32 v6, v6, v5
	v_ldexp_f32 v5, v7, v5
	v_add_f32_e32 v7, -1.0, v6
	v_add_f32_e32 v17, 1.0, v6
	v_add_f32_e32 v15, 1.0, v7
	v_add_f32_e32 v18, -1.0, v17
	v_sub_f32_e32 v15, v6, v15
	v_sub_f32_e32 v6, v6, v18
	v_add_f32_e32 v15, v5, v15
	v_add_f32_e32 v5, v5, v6
	v_add_f32_e32 v6, v17, v5
	v_rcp_f32_e32 v18, v6
	v_add_f32_e32 v16, v7, v15
	v_sub_f32_e32 v7, v16, v7
	v_sub_f32_e32 v7, v15, v7
	v_sub_f32_e32 v15, v6, v17
	v_sub_f32_e32 v5, v5, v15
	v_mul_f32_e32 v15, v16, v18
	v_mul_f32_e32 v17, v6, v15
	v_fma_f32 v19, v15, v6, -v17
	v_fmac_f32_e32 v19, v15, v5
	v_add_f32_e32 v20, v17, v19
	v_sub_f32_e32 v21, v16, v20
	v_sub_f32_e32 v16, v16, v21
	v_sub_f32_e32 v17, v20, v17
	v_sub_f32_e32 v16, v16, v20
	v_add_f32_e32 v7, v7, v16
	v_sub_f32_e32 v16, v17, v19
	v_add_f32_e32 v7, v16, v7
	v_add_f32_e32 v16, v21, v7
	v_mul_f32_e32 v17, v18, v16
	v_mul_f32_e32 v19, v6, v17
	v_fma_f32 v6, v17, v6, -v19
	v_fmac_f32_e32 v6, v17, v5
	v_sub_f32_e32 v5, v21, v16
	v_add_f32_e32 v5, v7, v5
	v_add_f32_e32 v7, v19, v6
	v_sub_f32_e32 v20, v16, v7
	v_sub_f32_e32 v16, v16, v20
	v_sub_f32_e32 v19, v7, v19
	v_sub_f32_e32 v7, v16, v7
	v_add_f32_e32 v5, v5, v7
	v_sub_f32_e32 v6, v19, v6
	v_cvt_f32_i32_e32 v4, v4
	v_add_f32_e32 v5, v6, v5
	v_add_f32_e32 v6, v15, v17
	v_add_f32_e32 v5, v20, v5
	v_sub_f32_e32 v7, v6, v15
	v_mul_f32_e32 v5, v18, v5
	v_sub_f32_e32 v7, v17, v7
	v_add_f32_e32 v5, v7, v5
	v_mul_f32_e32 v17, 0x3f317218, v4
	v_add_f32_e32 v7, v6, v5
	v_fma_f32 v18, v4, s13, -v17
	v_mul_f32_e32 v15, v7, v7
	v_fmac_f32_e32 v18, 0xb102e308, v4
	v_sub_f32_e32 v4, v7, v6
	v_fmamk_f32 v16, v15, 0x3e9b6dac, v160
	v_sub_f32_e32 v4, v5, v4
	v_add_f32_e32 v5, v17, v18
	v_fmaak_f32 v16, v15, v16, 0x3f2aaada
	v_sub_f32_e32 v6, v5, v17
	v_ldexp_f32 v17, v7, 1
	v_mul_f32_e32 v7, v7, v15
	v_mul_f32_e32 v7, v7, v16
	v_add_f32_e32 v15, v17, v7
	v_sub_f32_e32 v16, v15, v17
	v_ldexp_f32 v4, v4, 1
	v_sub_f32_e32 v7, v7, v16
	v_add_f32_e32 v4, v4, v7
	v_add_f32_e32 v7, v15, v4
	v_sub_f32_e32 v15, v7, v15
	v_sub_f32_e32 v4, v4, v15
	v_add_f32_e32 v15, v5, v7
	v_sub_f32_e32 v16, v15, v5
	v_sub_f32_e32 v17, v15, v16
	v_sub_f32_e32 v6, v18, v6
	v_sub_f32_e32 v5, v5, v17
	v_sub_f32_e32 v7, v7, v16
	v_add_f32_e32 v5, v7, v5
	v_add_f32_e32 v7, v6, v4
	v_sub_f32_e32 v16, v7, v6
	v_sub_f32_e32 v17, v7, v16
	v_sub_f32_e32 v6, v6, v17
	v_sub_f32_e32 v4, v4, v16
	v_add_f32_e32 v5, v7, v5
	v_add_f32_e32 v4, v4, v6
	v_add_f32_e32 v6, v15, v5
	v_sub_f32_e32 v7, v6, v15
	v_sub_f32_e32 v5, v5, v7
	v_add_f32_e32 v4, v4, v5
	v_add_f32_e32 v5, v85, v8
	v_mul_f32_e32 v5, 0xbfb8aa3b, v5
	v_exp_f32_e32 v5, v5
	v_add_f32_e32 v4, v6, v4
	v_cmp_neq_f32_e64 s[6:7], s14, v13
	v_add_f32_e32 v5, 1.0, v5
	v_rcp_f32_e32 v5, v5
	v_cndmask_b32_e64 v4, v177, v4, s[6:7]
	v_cmp_ngt_f32_e64 s[6:7], -1.0, v13
	v_mul_f32_e32 v5, 0xc1000000, v5
	s_nop 0
	v_cndmask_b32_e64 v4, v178, v4, s[6:7]
	v_cmp_neq_f32_e64 s[6:7], -1.0, v13
	s_nop 1
	v_cndmask_b32_e64 v4, v179, v4, s[6:7]
	v_cmp_lt_f32_e64 s[6:7], |v13|, s15
	s_nop 1
	v_cndmask_b32_e64 v4, v4, v13, s[6:7]
	v_mul_f32_e32 v5, v4, v5
	v_add_f32_e32 v6, v5, v5
	v_mul_f32_e32 v6, 0x3fb8aa3b, v6
	v_exp_f32_e32 v6, v6
	v_mul_f32_e32 v5, 0x3fb8aa3b, v5
	v_exp_f32_e32 v5, v5
	v_sub_f32_e32 v6, 1.0, v6
	v_mul_f32_e32 v7, 0x4f800000, v6
	v_cmp_gt_f32_e64 s[6:7], s16, v6
	v_cndmask_b32_e32 v5, 1.0, v5, vcc
	s_nop 0
	v_cndmask_b32_e64 v6, v6, v7, s[6:7]
	v_sqrt_f32_e32 v7, v6
	s_nop 0
	v_add_u32_e32 v8, -1, v7
	v_fma_f32 v12, -v8, v7, v6
	v_cmp_ge_f32_e64 s[8:9], 0, v12
	v_add_u32_e32 v12, 1, v7
	s_nop 0
	v_cndmask_b32_e64 v8, v7, v8, s[8:9]
	v_fma_f32 v7, -v12, v7, v6
	v_cmp_lt_f32_e64 s[8:9], 0, v7
	s_nop 1
	v_cndmask_b32_e64 v7, v8, v12, s[8:9]
	v_mul_f32_e32 v12, 0x37800000, v7
	v_cndmask_b32_e64 v7, v7, v12, s[6:7]
	v_cmp_class_f32_e64 s[6:7], v6, v161
	ds_read_b32 v8, v48 offset:17344
	s_waitcnt lgkmcnt(0)
	v_mul_f32_e32 v0, v8, v0
	v_cndmask_b32_e64 v6, v7, v6, s[6:7]
	v_add_f32_e32 v7, v85, v9
	v_mul_f32_e32 v7, 0xbfb8aa3b, v7
	v_exp_f32_e32 v7, v7
	v_mul_f32_e32 v0, v0, v6
	v_cndmask_b32_e32 v0, 0, v0, vcc
	ds_write_b32 v48, v5 offset:192
	ds_write_b32 v48, v0 offset:33728
	v_add_f32_e32 v6, 1.0, v7
	v_rcp_f32_e32 v6, v6
	v_add_f32_e32 v0, 1.0, v1
	v_rcp_f32_e32 v0, v0
	v_mul_f32_e32 v6, 0xc1000000, v6
	v_mul_f32_e32 v6, v4, v6
	v_add_f32_e32 v7, v6, v6
	v_mul_f32_e32 v7, 0x3fb8aa3b, v7
	v_exp_f32_e32 v7, v7
	v_mul_f32_e32 v6, 0x3fb8aa3b, v6
	v_exp_f32_e32 v6, v6
	v_sub_f32_e32 v1, 1.0, v7
	v_mul_f32_e32 v5, 0x4f800000, v1
	v_cmp_gt_f32_e32 vcc, s16, v1
	s_nop 1
	v_cndmask_b32_e32 v1, v1, v5, vcc
	v_sqrt_f32_e32 v5, v1
	s_nop 0
	v_add_u32_e32 v7, -1, v5
	v_fma_f32 v8, -v7, v5, v1
	v_cmp_ge_f32_e64 s[6:7], 0, v8
	v_add_u32_e32 v8, 1, v5
	s_nop 0
	v_cndmask_b32_e64 v7, v5, v7, s[6:7]
	v_fma_f32 v5, -v8, v5, v1
	v_cmp_lt_f32_e64 s[6:7], 0, v5
	s_nop 1
	v_cndmask_b32_e64 v5, v7, v8, s[6:7]
	v_mul_f32_e32 v8, 0x37800000, v5
	v_cndmask_b32_e32 v5, v5, v8, vcc
	v_cmp_class_f32_e32 vcc, v1, v161
	ds_read_b32 v7, v49 offset:17344
	s_waitcnt lgkmcnt(0)
; DI float sigm(float x) { return __builtin_amdgcn_rcpf(1.f + __expf(-x)); }
; DI void lru_tile(const Params& p, int layer, int isP, int sq, int tile, int nb, int pass, char*) {
;     ...
; #pragma unroll
;       for (int j = 0; j < 4; ++j) {
;         const int t = wid * 16 + fq * 4 + j;
;         float r = sigm(ar[j] + bav), ig = sigm(ai[j] + bxv);
;         float la = -8.f * r * sp;
;         float a = __expf(la);
;         float b = sqrtf(1.f - __expf(2.f * la)) * (ig * xcs[t * 64 + d]);
;         if (t0 + t >= T) { a = 1.f; b = 0.f; }
;         as_[t * 64 + d] = a;
;         bs_[t * 64 + d] = b;
;       }
;     }
;   }
;   __syncthreads();
;   const int c = tid & 63;
;   {
;     float A = 1.f, B = 0.f;
; #pragma unroll
;     for (int tt = 0; tt < 16; ++tt) {
;       float a = as_[(wid * 16 + tt) * 64 + c], b = bs_[(wid * 16 + tt) * 64 + c];
;       A *= a; B = a * B + b;
;     }
;     ab[(wid * 64 + c) * 2] = A;
;     ab[(wid * 64 + c) * 2 + 1] = B;
;   }
;   __syncthreads();
	v_mul_f32_e32 v0, v7, v0
	v_cndmask_b32_e32 v1, v5, v1, vcc
	v_add_f32_e32 v5, v85, v10
	v_mul_f32_e32 v5, 0xbfb8aa3b, v5
	v_exp_f32_e32 v5, v5
	v_mul_f32_e32 v0, v0, v1
	v_cndmask_b32_e64 v1, 1.0, v6, s[0:1]
	v_cndmask_b32_e64 v0, 0, v0, s[0:1]
	v_add_f32_e32 v5, 1.0, v5
	v_rcp_f32_e32 v5, v5
	ds_write_b32 v49, v1 offset:192
	ds_write_b32 v49, v0 offset:33728
	v_add_f32_e32 v0, 1.0, v2
	v_rcp_f32_e32 v0, v0
	v_mul_f32_e32 v5, 0xc1000000, v5
	v_mul_f32_e32 v5, v4, v5
	v_add_f32_e32 v6, v5, v5
	v_mul_f32_e32 v6, 0x3fb8aa3b, v6
	v_exp_f32_e32 v6, v6
	v_mul_f32_e32 v5, 0x3fb8aa3b, v5
	v_exp_f32_e32 v5, v5
	v_sub_f32_e32 v1, 1.0, v6
	v_mul_f32_e32 v2, 0x4f800000, v1
	v_cmp_gt_f32_e32 vcc, s16, v1
	s_nop 1
	v_cndmask_b32_e32 v1, v1, v2, vcc
	v_sqrt_f32_e32 v2, v1
	s_nop 0
	v_add_u32_e32 v6, -1, v2
	v_fma_f32 v7, -v6, v2, v1
	v_cmp_ge_f32_e64 s[0:1], 0, v7
	v_add_u32_e32 v7, 1, v2
	s_nop 0
	v_cndmask_b32_e64 v6, v2, v6, s[0:1]
	v_fma_f32 v2, -v7, v2, v1
	v_cmp_lt_f32_e64 s[0:1], 0, v2
	s_nop 1
	v_cndmask_b32_e64 v2, v6, v7, s[0:1]
	v_mul_f32_e32 v7, 0x37800000, v2
	v_cndmask_b32_e32 v2, v2, v7, vcc
	v_cmp_class_f32_e32 vcc, v1, v161
	ds_read_b32 v6, v50 offset:17344
	s_waitcnt lgkmcnt(0)
	v_mul_f32_e32 v0, v0, v6
	v_cndmask_b32_e32 v1, v2, v1, vcc
	v_add_f32_e32 v2, v85, v11
	v_mul_f32_e32 v2, 0xbfb8aa3b, v2
	v_exp_f32_e32 v2, v2
	v_mul_f32_e32 v0, v0, v1
	v_cndmask_b32_e64 v1, 1.0, v5, s[2:3]
	v_cndmask_b32_e64 v0, 0, v0, s[2:3]
	v_add_f32_e32 v2, 1.0, v2
	v_rcp_f32_e32 v2, v2
	ds_write_b32 v50, v1 offset:192
	ds_write_b32 v50, v0 offset:33728
	v_add_f32_e32 v0, 1.0, v3
	v_rcp_f32_e32 v0, v0
	v_mul_f32_e32 v2, 0xc1000000, v2
	v_mul_f32_e32 v2, v4, v2
	v_add_f32_e32 v4, v2, v2
	v_mul_f32_e32 v4, 0x3fb8aa3b, v4
	v_exp_f32_e32 v4, v4
	v_mul_f32_e32 v2, 0x3fb8aa3b, v2
	v_exp_f32_e32 v2, v2
	v_sub_f32_e32 v1, 1.0, v4
	v_mul_f32_e32 v3, 0x4f800000, v1
	v_cmp_gt_f32_e32 vcc, s16, v1
	s_nop 1
	v_cndmask_b32_e32 v1, v1, v3, vcc
	v_sqrt_f32_e32 v3, v1
	s_nop 0
	v_add_u32_e32 v4, -1, v3
	v_fma_f32 v5, -v4, v3, v1
	v_cmp_ge_f32_e64 s[0:1], 0, v5
	v_add_u32_e32 v5, 1, v3
	s_nop 0
	v_cndmask_b32_e64 v4, v3, v4, s[0:1]
	v_fma_f32 v3, -v5, v3, v1
	v_cmp_lt_f32_e64 s[0:1], 0, v3
	s_nop 1
	v_cndmask_b32_e64 v3, v4, v5, s[0:1]
	ds_read_b32 v4, v51 offset:17344
	v_mul_f32_e32 v5, 0x37800000, v3
	v_cndmask_b32_e32 v3, v3, v5, vcc
	v_cmp_class_f32_e32 vcc, v1, v161
	s_lshl_b32 s0, s47, 9
	s_waitcnt lgkmcnt(0)
	v_mul_f32_e32 v0, v0, v4
	v_cndmask_b32_e32 v1, v3, v1, vcc
	v_mul_f32_e32 v0, v1, v0
	v_cndmask_b32_e64 v1, 1.0, v2, s[4:5]
	v_cndmask_b32_e64 v0, 0, v0, s[4:5]
	ds_write_b32 v51, v1 offset:192
	ds_write_b32 v51, v0 offset:33728
	v_lshlrev_b32_e32 v0, 2, v72
	v_lshl_or_b32 v1, s47, 12, v0
	v_add_u32_e32 v1, 0x80, v1
	s_waitcnt lgkmcnt(0)
	s_barrier
	ds_read2st64_b32 v[2:3], v1 offset0:131 offset1:132
	ds_read2st64_b32 v[4:5], v1 offset1:1
	ds_read2st64_b32 v[6:7], v1 offset0:2 offset1:3
	ds_read2st64_b32 v[8:9], v1 offset0:4 offset1:5
	ds_read2st64_b32 v[10:11], v1 offset0:6 offset1:7
	ds_read2st64_b32 v[12:13], v1 offset0:133 offset1:134
	ds_read2st64_b32 v[14:15], v1 offset0:135 offset1:136
	ds_read2st64_b32 v[16:17], v1 offset0:137 offset1:138
	s_waitcnt lgkmcnt(6)
	v_fma_f32 v18, 0, v4, v2
	v_fmac_f32_e32 v3, v18, v5
	s_waitcnt lgkmcnt(2)
	v_fma_f32 v3, v3, v6, v12
	v_fmac_f32_e32 v13, v3, v7
	s_waitcnt lgkmcnt(1)
	v_fma_f32 v3, v13, v8, v14
	v_fmac_f32_e32 v15, v3, v9
	s_waitcnt lgkmcnt(0)
	v_fma_f32 v3, v15, v10, v16
	v_mul_f32_e32 v2, v4, v5
	v_fmac_f32_e32 v17, v3, v11
	ds_read2st64_b32 v[4:5], v1 offset0:139 offset1:140
	ds_read2st64_b32 v[12:13], v1 offset0:8 offset1:9
	ds_read2st64_b32 v[14:15], v1 offset0:10 offset1:11
	ds_read2st64_b32 v[18:19], v1 offset0:12 offset1:13
	ds_read2st64_b32 v[20:21], v1 offset0:14 offset1:15
	ds_read2st64_b32 v[22:23], v1 offset0:141 offset1:142
	ds_read2st64_b32 v[24:25], v1 offset0:143 offset1:144
	ds_read2st64_b32 v[26:27], v1 offset0:145 offset1:146
	s_waitcnt lgkmcnt(6)
	v_fmac_f32_e32 v4, v17, v12
	v_mov_b32_e32 v3, v4
	v_mov_b32_e32 v16, v6
	v_mov_b32_e32 v17, v13
	v_mov_b32_e32 v4, v7
	v_mul_f32_e32 v6, v2, v6
	v_pk_fma_f32 v[2:3], v[2:3], v[16:17], v[4:5]
	v_mul_f32_e32 v6, v6, v7
	v_mov_b32_e32 v7, v3
	v_mov_b32_e32 v2, v8
	s_waitcnt lgkmcnt(5)
	v_mov_b32_e32 v3, v14
	v_pk_mul_f32 v[4:5], v[6:7], v[2:3]
	v_mov_b32_e32 v8, v9
	v_mov_b32_e32 v16, v9
	s_waitcnt lgkmcnt(2)
	v_mov_b32_e32 v17, v22
	v_pk_mul_f32 v[4:5], v[4:5], v[8:9]
	v_pk_fma_f32 v[2:3], v[6:7], v[2:3], v[16:17]
	s_addk_i32 s0, 0x80
	v_mov_b32_e32 v2, v4
	v_lshl_add_u32 v9, v128, 2, s0
	v_mov_b32_e32 v6, v10
	v_mov_b32_e32 v7, v15
	v_pk_mul_f32 v[4:5], v[4:5], v[10:11]
	v_mov_b32_e32 v8, v11
	v_mov_b32_e32 v22, v11
	v_pk_mul_f32 v[4:5], v[4:5], v[8:9]
	v_pk_fma_f32 v[2:3], v[2:3], v[6:7], v[22:23]
	v_mov_b32_e32 v8, v13
	v_mov_b32_e32 v5, v3
	v_mov_b32_e32 v2, v12
	v_mov_b32_e32 v3, v18
	v_pk_mul_f32 v[6:7], v[4:5], v[2:3]
	v_mov_b32_e32 v10, v13
	s_waitcnt lgkmcnt(1)
	v_mov_b32_e32 v11, v24
	v_pk_mul_f32 v[6:7], v[6:7], v[8:9]
	v_pk_fma_f32 v[2:3], v[4:5], v[2:3], v[10:11]
	v_mov_b32_e32 v4, v14
	v_mov_b32_e32 v2, v6
	v_mov_b32_e32 v5, v19
	v_pk_mul_f32 v[6:7], v[6:7], v[14:15]
	v_mov_b32_e32 v8, v15
	v_mov_b32_e32 v24, v15
	v_pk_mul_f32 v[6:7], v[6:7], v[8:9]
	v_pk_fma_f32 v[2:3], v[2:3], v[4:5], v[24:25]
	v_mov_b32_e32 v8, v19
	v_mov_b32_e32 v7, v3
	v_mov_b32_e32 v2, v18
	v_mov_b32_e32 v3, v20
	v_pk_mul_f32 v[4:5], v[6:7], v[2:3]
	v_mov_b32_e32 v10, v19
	s_waitcnt lgkmcnt(0)
	v_mov_b32_e32 v11, v26
	v_pk_mul_f32 v[4:5], v[4:5], v[8:9]
	v_pk_fma_f32 v[2:3], v[6:7], v[2:3], v[10:11]
	v_mov_b32_e32 v6, v21
	v_mov_b32_e32 v2, v4
	v_pk_mul_f32 v[4:5], v[4:5], v[20:21]
	v_mov_b32_e32 v26, v21
	v_pk_mul_f32 v[4:5], v[4:5], v[6:7]
	v_pk_fma_f32 v[2:3], v[2:3], v[20:21], v[26:27]
	s_cmp_gt_i32 s45, 0
	v_mov_b32_e32 v5, v3
	ds_write_b64 v9, v[4:5] offset:49920
	s_waitcnt lgkmcnt(0)
	s_barrier
; DI void lru_tile(const Params& p, int layer, int isP, int sq, int tile, int nb, int pass, char*) {
;     ...
;     float h = isP ? 0.f : p.state_lru[(long)(layer * NB_S + sq) * 512 + ch0 + c];
;     for (int i0 = 0; i0 < tile; i0 += 16) {
;       float2 e[16];
; #pragma unroll
;       for (int u = 0; u < 16; ++u)
;         e[u] = (i0 + u < tile) ? *(const float2*)(agg + ((long)(sq * NTILE_P + i0 + u) * 512 + ch0 + c) * 2) : make_float2(1.f, 0.f);
; #pragma unroll
;       for (int u = 0; u < 16; ++u) h = e[u].x * h + e[u].y;
;     }
;     for (int w = 0; w < wid; ++w) h = ab[(w * 64 + c) * 2] * h + ab[(w * 64 + c) * 2 + 1];
	s_cbranch_scc0 .LBB0_4794
	s_mul_i32 s0, s42, 0x41
	s_ashr_i32 s1, s0, 31
	s_lshl_b64 s[0:1], s[0:1], 12
	s_add_u32 s0, s63, s0
	v_lshlrev_b32_e32 v2, 3, v75
	v_mov_b32_e32 v3, v129
	s_addc_u32 s1, s88, s1
	v_lshl_add_u64 v[2:3], s[0:1], 0, v[2:3]
	v_mov_b32_e32 v36, 0
	s_waitcnt vmcnt(0)
	v_fma_f32 v36, v36, v132, v133
	s_cmpk_lt_i32 s45, 2
	s_cbranch_scc1 .LBB0_4795
	v_fma_f32 v36, v36, v134, v135
	s_cmpk_lt_i32 s45, 3
	s_cbranch_scc1 .LBB0_4795
	v_fma_f32 v36, v36, v136, v137
	s_cmpk_lt_i32 s45, 4
	s_cbranch_scc1 .LBB0_4795
	v_fma_f32 v36, v36, v138, v139
	s_cmpk_lt_i32 s45, 5
	s_cbranch_scc1 .LBB0_4795
	v_fma_f32 v36, v36, v140, v141
	s_cmpk_lt_i32 s45, 6
	s_cbranch_scc1 .LBB0_4795
	v_fma_f32 v36, v36, v142, v143
	s_cmpk_lt_i32 s45, 7
	s_cbranch_scc1 .LBB0_4795
	v_fma_f32 v36, v36, v144, v145
	s_cmpk_lt_i32 s45, 8
	s_cbranch_scc1 .LBB0_4795
	v_fma_f32 v36, v36, v146, v147
	s_cmpk_lt_i32 s45, 9
	s_cbranch_scc1 .LBB0_4795
	v_fma_f32 v36, v36, v148, v149
	s_cmpk_lt_i32 s45, 10
	s_cbranch_scc1 .LBB0_4795
	v_fma_f32 v36, v36, v150, v151
	s_cmpk_lt_i32 s45, 11
	s_cbranch_scc1 .LBB0_4795
	v_fma_f32 v36, v36, v152, v153
	s_cmpk_lt_i32 s45, 12
	s_cbranch_scc1 .LBB0_4795
	v_fma_f32 v36, v36, v154, v155
	s_cmpk_lt_i32 s45, 13
	s_cbranch_scc1 .LBB0_4795
	v_fma_f32 v36, v36, v156, v157
	s_cmpk_lt_i32 s45, 14
	s_cbranch_scc1 .LBB0_4795
	v_fma_f32 v36, v36, v180, v181
	s_cmpk_lt_i32 s45, 15
	s_cbranch_scc1 .LBB0_4795
	v_fma_f32 v36, v36, v182, v183
	s_cmpk_lt_i32 s45, 16
	s_cbranch_scc1 .LBB0_4795
	v_fma_f32 v36, v36, v184, v185
	s_cmpk_lt_i32 s45, 17
	s_cbranch_scc1 .LBB0_4795
	v_fma_f32 v36, v36, v186, v187
	s_cmpk_lt_i32 s45, 18
	s_cbranch_scc1 .LBB0_4795
	v_fma_f32 v36, v36, v188, v189
	s_cmpk_lt_i32 s45, 19
	s_cbranch_scc1 .LBB0_4795
	v_fma_f32 v36, v36, v190, v191
	s_cmpk_lt_i32 s45, 20
	s_cbranch_scc1 .LBB0_4795
	v_fma_f32 v36, v36, v192, v193
	s_cmpk_lt_i32 s45, 21
	s_cbranch_scc1 .LBB0_4795
	v_fma_f32 v36, v36, v194, v195
	s_cmpk_lt_i32 s45, 22
	s_cbranch_scc1 .LBB0_4795
	v_fma_f32 v36, v36, v196, v197
	s_cmpk_lt_i32 s45, 23
	s_cbranch_scc1 .LBB0_4795
	v_fma_f32 v36, v36, v198, v199
	s_cmpk_lt_i32 s45, 24
	s_cbranch_scc1 .LBB0_4795
	v_fma_f32 v36, v36, v200, v201
	s_cmpk_lt_i32 s45, 25
	s_cbranch_scc1 .LBB0_4795
	v_fma_f32 v36, v36, v202, v203
	s_cmpk_lt_i32 s45, 26
	s_cbranch_scc1 .LBB0_4795
	v_fma_f32 v36, v36, v204, v205
	s_cmpk_lt_i32 s45, 27
	s_cbranch_scc1 .LBB0_4795
	v_fma_f32 v36, v36, v206, v207
	s_cmpk_lt_i32 s45, 28
	s_cbranch_scc1 .LBB0_4795
	v_fma_f32 v36, v36, v208, v209
	s_cmpk_lt_i32 s45, 29
	s_cbranch_scc1 .LBB0_4795
	v_fma_f32 v36, v36, v210, v211
	s_cmpk_lt_i32 s45, 30
	s_cbranch_scc1 .LBB0_4795
	v_fma_f32 v36, v36, v212, v213
	s_cmpk_lt_i32 s45, 31
	s_cbranch_scc1 .LBB0_4795
	v_fma_f32 v36, v36, v214, v215
	s_cmpk_lt_i32 s45, 32
	s_cbranch_scc1 .LBB0_4795
	v_fma_f32 v36, v36, v216, v217
	s_cmpk_lt_i32 s45, 33
	s_cbranch_scc1 .LBB0_4795
	v_fma_f32 v36, v36, v218, v219
	s_cmpk_lt_i32 s45, 34
	s_cbranch_scc1 .LBB0_4795
	v_fma_f32 v36, v36, v220, v221
	s_cmpk_lt_i32 s45, 35
	s_cbranch_scc1 .LBB0_4795
	v_fma_f32 v36, v36, v222, v223
	s_cmpk_lt_i32 s45, 36
	s_cbranch_scc1 .LBB0_4795
	v_fma_f32 v36, v36, v224, v225
	s_cmpk_lt_i32 s45, 37
	s_cbranch_scc1 .LBB0_4795
	v_fma_f32 v36, v36, v226, v227
	s_cmpk_lt_i32 s45, 38
	s_cbranch_scc1 .LBB0_4795
	v_fma_f32 v36, v36, v228, v229
	s_cmpk_lt_i32 s45, 39
	s_cbranch_scc1 .LBB0_4795
	v_fma_f32 v36, v36, v230, v231
	s_cmpk_lt_i32 s45, 40
	s_cbranch_scc1 .LBB0_4795
	v_fma_f32 v36, v36, v232, v233
	s_cmpk_lt_i32 s45, 41
	s_cbranch_scc1 .LBB0_4795
	v_fma_f32 v36, v36, v234, v235
	s_cmpk_lt_i32 s45, 42
	s_cbranch_scc1 .LBB0_4795
	v_fma_f32 v36, v36, v236, v237
	s_cmpk_lt_i32 s45, 43
	s_cbranch_scc1 .LBB0_4795
	v_fma_f32 v36, v36, v238, v239
	s_cmpk_lt_i32 s45, 44
	s_cbranch_scc1 .LBB0_4795
	v_fma_f32 v36, v36, v240, v241
	s_cmpk_lt_i32 s45, 45
	s_cbranch_scc1 .LBB0_4795
	v_fma_f32 v36, v36, v242, v243
	s_cmpk_lt_i32 s45, 46
	s_cbranch_scc1 .LBB0_4795
	v_fma_f32 v36, v36, v244, v245
	s_cmpk_lt_i32 s45, 47
	s_cbranch_scc1 .LBB0_4795
	s_movk_i32 s11, 46
	s_mov_b64 s[0:1], 0x2e000
	v_lshl_add_u64 v[2:3], v[2:3], 0, s[0:1]
	s_branch .LBB0_4764
